# GEMM K-loops (SwiGLU, ProjGate, Branch): the last iteration of a workgroup's last unit runs from a copy that does not restage K-tiles 0/1 again (14 LDS-DMA pieces per wave removed, waits recounted)
# speedup vs baseline: 1.0076x; 1.0013x over previous
; #define PG8_STAGE(bufoff, gbase, voff) do { _Pragma("unroll") for (int _i = 0; _i < 2; ++_i) \
;         __builtin_amdgcn_global_load_lds((const unsigned*)((const char*)(gbase) + (voff)[_i]), (PG8_LAS unsigned*)(lds + (bufoff) + ldsw + _i * 8192), 16, 0, 0); } while (0)
; #define PG8_LDA(dst, b, h) do { _Pragma("unroll") for (int m = 0; m < 4; ++m) _Pragma("unroll") for (int k = 0; k < 2; ++k) dst[m][k] = *(const PG8_LAS bf16x8*)(lds + PG8_SA(b, h) + aoff + m * 2048 + k * 1024); } while (0)
; #define PG8_LDB(dst, b, h) do { _Pragma("unroll") for (int n = 0; n < 2; ++n) _Pragma("unroll") for (int k = 0; k < 2; ++k) dst[n][k] = *(const PG8_LAS bf16x8*)(lds + PG8_SB(b, h) + boff + n * 2048 + k * 1024); } while (0)
; #define PG8_MMA(ai, bj, At, Bt) do { __builtin_amdgcn_s_setprio(1); _Pragma("unroll") for (int m = 0; m < 4; ++m) _Pragma("unroll") for (int n = 0; n < 2; ++n) _Pragma("unroll") for (int k = 0; k < 2; ++k) \
;         acc[ai][bj][m][n] = __builtin_amdgcn_mfma_f32_16x16x32_bf16(Bt[n][k], At[m][k], acc[ai][bj][m][n], 0, 0, 0); __builtin_amdgcn_s_setprio(0); } while (0)
; #define PG8_WAIT_V(n) asm volatile("s_waitcnt vmcnt(" #n ")" ::: "memory")
; #define PG8_BAR __builtin_amdgcn_s_barrier()
; template <class Epi, class Sched, bool ALIGN_EPI = false, bool SP2 = false>
; __device__ __forceinline__ void gemm_phase(PG8_LAS unsigned char* lds, const Gemm g, const Sched& S, const Epi& E) {
;     ...
;         for (int t = 0; t < nt; t += 2) {
;             const bool last = (t == nt - 2);
;             const char* a1 = cA + (size_t)(t + 1) * kstep;
;             const char* a2 = last ? nA : cA + (size_t)(t + 2) * kstep; const char* b2 = last ? nB : cB + (size_t)(t + 2) * kstep;
;             const char* a3 = a2 + kstep; const char* b3 = b2 + kstep;
;             if (last && has_next) S.a_ready(nxt);
;             if constexpr (SP2) {
;             PG8_LDB(B0, 0, 0); PG8_LDB(B1, 0, 1); PG8_SCHED; PG8_LDA(At, 0, 0); PG8_STAGE(PG8_SA(1, 1), a1 + hstep, voffA);
;             PG8_WAIT_V(8); PG8_WAIT_L(0); PG8_BAR; PG8_MMA(0, 0, At, B0); PG8_MMA(0, 1, At, B1); PG8_BAR; PG8_SCHED;
;             PG8_LDA(At, 0, 1); PG8_STAGE(PG8_SB(0, 0), b2, voffB); PG8_STAGE(PG8_SB(0, 1), b2 + hstep, voffB); PG8_STAGE(PG8_SA(0, 0), a2, voffA);
;             PG8_WAIT_V(8); PG8_WAIT_L(0); PG8_BAR; PG8_MMA(1, 0, At, B0); PG8_MMA(1, 1, At, B1); PG8_BAR; PG8_SCHED;
.LBB0_49:
	s_add_u32 s40, s0, 0xfffe0080
	s_addc_u32 s41, s1, -1
	s_add_i32 s65, 0, 0x10000
	s_cmp_eq_u32 s64, 4
	s_cselect_b32 s43, s19, s41
	s_cselect_b32 s42, s60, s40
	s_cselect_b32 s41, s17, s63
	s_cselect_b32 s40, s61, s62
	s_add_i32 s68, 0, 0x14000
	v_add_u32_e32 v144, s65, v248
	v_add_u32_e32 v160, s68, v248
	ds_read_b128 v[132:135], v144
	ds_read_b128 v[136:139], v144 offset:1024
	ds_read_b128 v[140:143], v144 offset:2048
	ds_read_b128 v[144:147], v144 offset:3072
	ds_read_b128 v[148:151], v160
	ds_read_b128 v[152:155], v160 offset:1024
	ds_read_b128 v[156:159], v160 offset:2048
	ds_read_b128 v[160:163], v160 offset:3072
	v_lshl_add_u64 v[210:211], s[0:1], 0, v[206:207]
	s_add_i32 m0, s51, 0xc000
	ds_read_b128 v[164:167], v250
	ds_read_b128 v[168:171], v250 offset:1024
	ds_read_b128 v[172:175], v250 offset:2048
	ds_read_b128 v[176:179], v250 offset:3072
	ds_read_b128 v[180:183], v250 offset:4096
	ds_read_b128 v[184:187], v250 offset:5120
	ds_read_b128 v[188:191], v250 offset:6144
	ds_read_b128 v[192:195], v250 offset:7168
	global_load_lds_dwordx4 v[210:211], off
	v_lshl_add_u64 v[210:211], s[0:1], 0, v[208:209]
	s_add_i32 m0, s51, 0xe000
	s_nop 0
	global_load_lds_dwordx4 v[210:211], off
	s_waitcnt vmcnt(8)
	s_waitcnt lgkmcnt(0)
	v_mfma_f32_16x16x32_bf16 v[128:131], v[132:135], v[164:167], v[128:131]
	v_mfma_f32_16x16x32_bf16 v[124:127], v[140:143], v[164:167], v[124:127]
	v_mfma_f32_16x16x32_bf16 v[116:119], v[132:135], v[172:175], v[116:119]
	v_mfma_f32_16x16x32_bf16 v[108:111], v[140:143], v[172:175], v[108:111]
	s_barrier
	s_setprio 1
	v_mfma_f32_16x16x32_bf16 v[100:103], v[132:135], v[180:183], v[100:103]
	v_mfma_f32_16x16x32_bf16 v[92:95], v[140:143], v[180:183], v[92:95]
	v_mfma_f32_16x16x32_bf16 v[84:87], v[132:135], v[188:191], v[84:87]
	v_mfma_f32_16x16x32_bf16 v[76:79], v[140:143], v[188:191], v[76:79]
	v_mfma_f32_16x16x32_bf16 v[128:131], v[136:139], v[168:171], v[128:131]
	v_mfma_f32_16x16x32_bf16 v[124:127], v[144:147], v[168:171], v[124:127]
	v_mfma_f32_16x16x32_bf16 v[116:119], v[136:139], v[176:179], v[116:119]
	v_mfma_f32_16x16x32_bf16 v[108:111], v[144:147], v[176:179], v[108:111]
	v_mfma_f32_16x16x32_bf16 v[100:103], v[136:139], v[184:187], v[100:103]
	v_mfma_f32_16x16x32_bf16 v[92:95], v[144:147], v[184:187], v[92:95]
	v_mfma_f32_16x16x32_bf16 v[84:87], v[136:139], v[192:195], v[84:87]
	v_mfma_f32_16x16x32_bf16 v[76:79], v[144:147], v[192:195], v[76:79]
	s_setprio 0
	s_setprio 1
	v_mfma_f32_16x16x32_bf16 v[120:123], v[148:151], v[164:167], v[120:123]
	v_mfma_f32_16x16x32_bf16 v[112:115], v[156:159], v[164:167], v[112:115]
	v_mfma_f32_16x16x32_bf16 v[104:107], v[148:151], v[172:175], v[104:107]
	v_mfma_f32_16x16x32_bf16 v[96:99], v[156:159], v[172:175], v[96:99]
	v_mfma_f32_16x16x32_bf16 v[88:91], v[148:151], v[180:183], v[88:91]
	v_mfma_f32_16x16x32_bf16 v[80:83], v[156:159], v[180:183], v[80:83]
	v_mfma_f32_16x16x32_bf16 v[72:75], v[148:151], v[188:191], v[72:75]
	v_mfma_f32_16x16x32_bf16 v[68:71], v[156:159], v[188:191], v[68:71]
	v_mfma_f32_16x16x32_bf16 v[120:123], v[152:155], v[168:171], v[120:123]
	v_mfma_f32_16x16x32_bf16 v[112:115], v[160:163], v[168:171], v[112:115]
	v_mfma_f32_16x16x32_bf16 v[104:107], v[152:155], v[176:179], v[104:107]
	v_mfma_f32_16x16x32_bf16 v[96:99], v[160:163], v[176:179], v[96:99]
	v_mfma_f32_16x16x32_bf16 v[88:91], v[152:155], v[184:187], v[88:91]
	v_mfma_f32_16x16x32_bf16 v[80:83], v[160:163], v[184:187], v[80:83]
	v_mfma_f32_16x16x32_bf16 v[72:75], v[152:155], v[192:195], v[72:75]
	v_mfma_f32_16x16x32_bf16 v[68:71], v[160:163], v[192:195], v[68:71]
	s_setprio 0
	s_barrier
	s_add_i32 s65, s65, s50
	v_lshl_add_u64 v[210:211], s[40:41], 0, v[196:197]
	s_mov_b32 m0, s65
	ds_read_b128 v[164:167], v250 offset:16384
	ds_read_b128 v[168:171], v250 offset:17408
	ds_read_b128 v[172:175], v250 offset:18432
	ds_read_b128 v[176:179], v250 offset:19456
	ds_read_b128 v[180:183], v250 offset:20480
	ds_read_b128 v[184:187], v250 offset:21504
	ds_read_b128 v[188:191], v250 offset:22528
	ds_read_b128 v[192:195], v250 offset:23552
	global_load_lds_dwordx4 v[210:211], off
	s_add_i32 m0, s65, 0x2000
	s_add_u32 s66, s40, 0x20000
	v_lshl_add_u64 v[212:213], s[40:41], 0, v[32:33]
	s_addc_u32 s67, s41, 0
	s_add_i32 s65, s68, s50
	global_load_lds_dwordx4 v[212:213], off
	v_lshl_add_u64 v[214:215], s[66:67], 0, v[196:197]
	s_mov_b32 m0, s65
	v_lshl_add_u64 v[216:217], s[42:43], 0, v[202:203]
	global_load_lds_dwordx4 v[214:215], off
	v_lshl_add_u64 v[214:215], s[66:67], 0, v[32:33]
	s_add_i32 m0, s65, 0x2000
	s_nop 0
	global_load_lds_dwordx4 v[214:215], off
	v_lshl_add_u64 v[214:215], s[42:43], 0, v[204:205]
	s_mov_b32 m0, s51
	s_nop 0
	global_load_lds_dwordx4 v[214:215], off
	s_mov_b32 m0, s52
	s_nop 0
	global_load_lds_dwordx4 v[216:217], off
	s_waitcnt vmcnt(8)
	s_waitcnt lgkmcnt(0)
	v_mfma_f32_16x16x32_bf16 v[64:67], v[132:135], v[164:167], v[64:67]
	v_mfma_f32_16x16x32_bf16 v[60:63], v[140:143], v[164:167], v[60:63]
	v_mfma_f32_16x16x32_bf16 v[52:55], v[132:135], v[172:175], v[52:55]
	v_mfma_f32_16x16x32_bf16 v[44:47], v[140:143], v[172:175], v[44:47]
	s_barrier
; #define PG8_STAGE(bufoff, gbase, voff) do { _Pragma("unroll") for (int _i = 0; _i < 2; ++_i) \
;         __builtin_amdgcn_global_load_lds((const unsigned*)((const char*)(gbase) + (voff)[_i]), (PG8_LAS unsigned*)(lds + (bufoff) + ldsw + _i * 8192), 16, 0, 0); } while (0)
; #define PG8_LDA(dst, b, h) do { _Pragma("unroll") for (int m = 0; m < 4; ++m) _Pragma("unroll") for (int k = 0; k < 2; ++k) dst[m][k] = *(const PG8_LAS bf16x8*)(lds + PG8_SA(b, h) + aoff + m * 2048 + k * 1024); } while (0)
; #define PG8_LDB(dst, b, h) do { _Pragma("unroll") for (int n = 0; n < 2; ++n) _Pragma("unroll") for (int k = 0; k < 2; ++k) dst[n][k] = *(const PG8_LAS bf16x8*)(lds + PG8_SB(b, h) + boff + n * 2048 + k * 1024); } while (0)
; #define PG8_MMA(ai, bj, At, Bt) do { __builtin_amdgcn_s_setprio(1); _Pragma("unroll") for (int m = 0; m < 4; ++m) _Pragma("unroll") for (int n = 0; n < 2; ++n) _Pragma("unroll") for (int k = 0; k < 2; ++k) \
;         acc[ai][bj][m][n] = __builtin_amdgcn_mfma_f32_16x16x32_bf16(Bt[n][k], At[m][k], acc[ai][bj][m][n], 0, 0, 0); __builtin_amdgcn_s_setprio(0); } while (0)
; #define PG8_WAIT_V(n) asm volatile("s_waitcnt vmcnt(" #n ")" ::: "memory")
; #define PG8_WAIT_L(n) asm volatile("s_waitcnt lgkmcnt(" #n ")" ::: "memory")
; #define PG8_BAR __builtin_amdgcn_s_barrier()
; #define PG8_SCHED __builtin_amdgcn_sched_barrier(0)
; template <class Epi, class Sched, bool ALIGN_EPI = false, bool SP2 = false>
; __device__ __forceinline__ void gemm_phase(PG8_LAS unsigned char* lds, const Gemm g, const Sched& S, const Epi& E) {
;     ...
;             PG8_WAIT_V(8); PG8_WAIT_L(0); PG8_BAR; PG8_MMA(1, 0, At, B0); PG8_MMA(1, 1, At, B1); PG8_BAR; PG8_SCHED;
;             PG8_LDB(B0, 1, 0); PG8_LDB(B1, 1, 1); PG8_SCHED; PG8_LDA(At, 1, 0); PG8_STAGE(PG8_SA(0, 1), a2 + hstep, voffA);
;             PG8_WAIT_V(8); PG8_WAIT_L(0); PG8_BAR; PG8_MMA(0, 0, At, B0); PG8_MMA(0, 1, At, B1); PG8_BAR; PG8_SCHED;
	s_setprio 1
	v_mfma_f32_16x16x32_bf16 v[36:39], v[132:135], v[180:183], v[36:39]
	v_mfma_f32_16x16x32_bf16 v[24:27], v[140:143], v[180:183], v[24:27]
	v_mfma_f32_16x16x32_bf16 v[16:19], v[132:135], v[188:191], v[16:19]
	v_mfma_f32_16x16x32_bf16 v[8:11], v[140:143], v[188:191], v[8:11]
	v_mfma_f32_16x16x32_bf16 v[64:67], v[136:139], v[168:171], v[64:67]
	v_mfma_f32_16x16x32_bf16 v[60:63], v[144:147], v[168:171], v[60:63]
	v_mfma_f32_16x16x32_bf16 v[52:55], v[136:139], v[176:179], v[52:55]
	v_mfma_f32_16x16x32_bf16 v[44:47], v[144:147], v[176:179], v[44:47]
	v_mfma_f32_16x16x32_bf16 v[36:39], v[136:139], v[184:187], v[36:39]
	v_mfma_f32_16x16x32_bf16 v[24:27], v[144:147], v[184:187], v[24:27]
	v_mfma_f32_16x16x32_bf16 v[16:19], v[136:139], v[192:195], v[16:19]
	v_mfma_f32_16x16x32_bf16 v[8:11], v[144:147], v[192:195], v[8:11]
	s_setprio 0
	s_setprio 1
	v_mfma_f32_16x16x32_bf16 v[56:59], v[148:151], v[164:167], v[56:59]
	v_mfma_f32_16x16x32_bf16 v[48:51], v[156:159], v[164:167], v[48:51]
	v_mfma_f32_16x16x32_bf16 v[40:43], v[148:151], v[172:175], v[40:43]
	v_mfma_f32_16x16x32_bf16 v[28:31], v[156:159], v[172:175], v[28:31]
	v_mfma_f32_16x16x32_bf16 v[20:23], v[148:151], v[180:183], v[20:23]
	v_mfma_f32_16x16x32_bf16 v[12:15], v[156:159], v[180:183], v[12:15]
	v_mfma_f32_16x16x32_bf16 v[4:7], v[148:151], v[188:191], v[4:7]
	v_mfma_f32_16x16x32_bf16 v[0:3], v[156:159], v[188:191], v[0:3]
	v_mfma_f32_16x16x32_bf16 v[56:59], v[152:155], v[168:171], v[56:59]
	v_mfma_f32_16x16x32_bf16 v[48:51], v[160:163], v[168:171], v[48:51]
	v_mfma_f32_16x16x32_bf16 v[40:43], v[152:155], v[176:179], v[40:43]
	v_mfma_f32_16x16x32_bf16 v[28:31], v[160:163], v[176:179], v[28:31]
	v_mfma_f32_16x16x32_bf16 v[20:23], v[152:155], v[184:187], v[20:23]
	v_mfma_f32_16x16x32_bf16 v[12:15], v[160:163], v[184:187], v[12:15]
	v_mfma_f32_16x16x32_bf16 v[4:7], v[152:155], v[192:195], v[4:7]
	v_mfma_f32_16x16x32_bf16 v[0:3], v[160:163], v[192:195], v[0:3]
	s_setprio 0
	s_barrier
	s_add_i32 s65, 0, 0x18000
	s_add_i32 s66, 0, 0x1c000
	v_add_u32_e32 v144, s65, v248
	v_add_u32_e32 v160, s66, v248
	ds_read_b128 v[132:135], v144
	ds_read_b128 v[136:139], v144 offset:1024
	ds_read_b128 v[140:143], v144 offset:2048
	ds_read_b128 v[144:147], v144 offset:3072
	ds_read_b128 v[148:151], v160
	ds_read_b128 v[152:155], v160 offset:1024
	ds_read_b128 v[156:159], v160 offset:2048
	ds_read_b128 v[160:163], v160 offset:3072
	s_add_u32 s42, s42, 0x20000
	s_addc_u32 s43, s43, 0
	s_mov_b32 m0, s53
	v_lshl_add_u64 v[218:219], s[42:43], 0, v[204:205]
	ds_read_b128 v[164:167], v250 offset:32768
	ds_read_b128 v[168:171], v250 offset:33792
	ds_read_b128 v[172:175], v250 offset:34816
	ds_read_b128 v[176:179], v250 offset:35840
	ds_read_b128 v[180:183], v250 offset:36864
	ds_read_b128 v[184:187], v250 offset:37888
	ds_read_b128 v[188:191], v250 offset:38912
	ds_read_b128 v[192:195], v250 offset:39936
	global_load_lds_dwordx4 v[218:219], off
	v_lshl_add_u64 v[218:219], s[42:43], 0, v[202:203]
	s_mov_b32 m0, s54
	s_nop 0
	global_load_lds_dwordx4 v[218:219], off
	s_waitcnt vmcnt(8)
	s_waitcnt lgkmcnt(0)
	v_mfma_f32_16x16x32_bf16 v[128:131], v[132:135], v[164:167], v[128:131]
	v_mfma_f32_16x16x32_bf16 v[124:127], v[140:143], v[164:167], v[124:127]
	v_mfma_f32_16x16x32_bf16 v[116:119], v[132:135], v[172:175], v[116:119]
	v_mfma_f32_16x16x32_bf16 v[108:111], v[140:143], v[172:175], v[108:111]
	s_barrier
	s_setprio 1
	v_mfma_f32_16x16x32_bf16 v[100:103], v[132:135], v[180:183], v[100:103]
	v_mfma_f32_16x16x32_bf16 v[92:95], v[140:143], v[180:183], v[92:95]
	v_mfma_f32_16x16x32_bf16 v[84:87], v[132:135], v[188:191], v[84:87]
	v_mfma_f32_16x16x32_bf16 v[76:79], v[140:143], v[188:191], v[76:79]
	v_mfma_f32_16x16x32_bf16 v[128:131], v[136:139], v[168:171], v[128:131]
	v_mfma_f32_16x16x32_bf16 v[124:127], v[144:147], v[168:171], v[124:127]
	v_mfma_f32_16x16x32_bf16 v[116:119], v[136:139], v[176:179], v[116:119]
	v_mfma_f32_16x16x32_bf16 v[108:111], v[144:147], v[176:179], v[108:111]
	v_mfma_f32_16x16x32_bf16 v[100:103], v[136:139], v[184:187], v[100:103]
	v_mfma_f32_16x16x32_bf16 v[92:95], v[144:147], v[184:187], v[92:95]
	v_mfma_f32_16x16x32_bf16 v[84:87], v[136:139], v[192:195], v[84:87]
	v_mfma_f32_16x16x32_bf16 v[76:79], v[144:147], v[192:195], v[76:79]
	s_setprio 0
	s_setprio 1
	v_mfma_f32_16x16x32_bf16 v[120:123], v[148:151], v[164:167], v[120:123]
	v_mfma_f32_16x16x32_bf16 v[112:115], v[156:159], v[164:167], v[112:115]
	v_mfma_f32_16x16x32_bf16 v[104:107], v[148:151], v[172:175], v[104:107]
	v_mfma_f32_16x16x32_bf16 v[96:99], v[156:159], v[172:175], v[96:99]
	v_mfma_f32_16x16x32_bf16 v[88:91], v[148:151], v[180:183], v[88:91]
	v_mfma_f32_16x16x32_bf16 v[80:83], v[156:159], v[180:183], v[80:83]
	v_mfma_f32_16x16x32_bf16 v[72:75], v[148:151], v[188:191], v[72:75]
	v_mfma_f32_16x16x32_bf16 v[68:71], v[156:159], v[188:191], v[68:71]
	v_mfma_f32_16x16x32_bf16 v[120:123], v[152:155], v[168:171], v[120:123]
	v_mfma_f32_16x16x32_bf16 v[112:115], v[160:163], v[168:171], v[112:115]
	v_mfma_f32_16x16x32_bf16 v[104:107], v[152:155], v[176:179], v[104:107]
	v_mfma_f32_16x16x32_bf16 v[96:99], v[160:163], v[176:179], v[96:99]
	v_mfma_f32_16x16x32_bf16 v[88:91], v[152:155], v[184:187], v[88:91]
	v_mfma_f32_16x16x32_bf16 v[80:83], v[160:163], v[184:187], v[80:83]
	v_mfma_f32_16x16x32_bf16 v[72:75], v[152:155], v[192:195], v[72:75]
	v_mfma_f32_16x16x32_bf16 v[68:71], v[160:163], v[192:195], v[68:71]
	s_setprio 0
	s_barrier
; #define PG8_STAGE(bufoff, gbase, voff) do { _Pragma("unroll") for (int _i = 0; _i < 2; ++_i) \
;         __builtin_amdgcn_global_load_lds((const unsigned*)((const char*)(gbase) + (voff)[_i]), (PG8_LAS unsigned*)(lds + (bufoff) + ldsw + _i * 8192), 16, 0, 0); } while (0)
; #define PG8_LDA(dst, b, h) do { _Pragma("unroll") for (int m = 0; m < 4; ++m) _Pragma("unroll") for (int k = 0; k < 2; ++k) dst[m][k] = *(const PG8_LAS bf16x8*)(lds + PG8_SA(b, h) + aoff + m * 2048 + k * 1024); } while (0)
; #define PG8_MMA(ai, bj, At, Bt) do { __builtin_amdgcn_s_setprio(1); _Pragma("unroll") for (int m = 0; m < 4; ++m) _Pragma("unroll") for (int n = 0; n < 2; ++n) _Pragma("unroll") for (int k = 0; k < 2; ++k) \
;         acc[ai][bj][m][n] = __builtin_amdgcn_mfma_f32_16x16x32_bf16(Bt[n][k], At[m][k], acc[ai][bj][m][n], 0, 0, 0); __builtin_amdgcn_s_setprio(0); } while (0)
; #define PG8_WAIT_V(n) asm volatile("s_waitcnt vmcnt(" #n ")" ::: "memory")
; #define PG8_WAIT_L(n) asm volatile("s_waitcnt lgkmcnt(" #n ")" ::: "memory")
; #define PG8_BAR __builtin_amdgcn_s_barrier()
; #define PG8_SCHED __builtin_amdgcn_sched_barrier(0)
; template <class Epi, class Sched, bool ALIGN_EPI = false, bool SP2 = false>
; __device__ __forceinline__ void gemm_phase(PG8_LAS unsigned char* lds, const Gemm g, const Sched& S, const Epi& E) {
;     ...
;         for (int t = 0; t < nt; t += 2) {
;             const bool last = (t == nt - 2);
;             const char* a1 = cA + (size_t)(t + 1) * kstep;
;             const char* a2 = last ? nA : cA + (size_t)(t + 2) * kstep; const char* b2 = last ? nB : cB + (size_t)(t + 2) * kstep;
;             const char* a3 = a2 + kstep; const char* b3 = b2 + kstep;
;             if (last && has_next) S.a_ready(nxt);
;     ...
;             PG8_WAIT_V(8); PG8_WAIT_L(0); PG8_BAR; PG8_MMA(0, 0, At, B0); PG8_MMA(0, 1, At, B1); PG8_BAR; PG8_SCHED;
;             PG8_LDA(At, 1, 1); PG8_STAGE(PG8_SB(1, 0), b3, voffB); PG8_STAGE(PG8_SB(1, 1), b3 + hstep, voffB); PG8_STAGE(PG8_SA(1, 0), a3, voffA);
;             PG8_WAIT_V(8); PG8_WAIT_L(0); PG8_BAR; PG8_MMA(1, 0, At, B0); PG8_MMA(1, 1, At, B1); PG8_BAR; PG8_SCHED;
	s_add_i32 s42, s65, s50
	v_lshl_add_u64 v[210:211], v[210:211], 0, s[36:37]
	s_mov_b32 m0, s42
	ds_read_b128 v[164:167], v250 offset:49152
	ds_read_b128 v[168:171], v250 offset:50176
	ds_read_b128 v[172:175], v250 offset:51200
	ds_read_b128 v[176:179], v250 offset:52224
	ds_read_b128 v[180:183], v250 offset:53248
	ds_read_b128 v[184:187], v250 offset:54272
	ds_read_b128 v[188:191], v250 offset:55296
	ds_read_b128 v[192:195], v250 offset:56320
	global_load_lds_dwordx4 v[210:211], off
	s_add_i32 m0, s42, 0x2000
	s_add_u32 s40, s40, 0x20080
	v_lshl_add_u64 v[210:211], v[212:213], 0, s[36:37]
	s_addc_u32 s41, s41, 0
	s_add_i32 s42, s66, s50
	global_load_lds_dwordx4 v[210:211], off
	v_lshl_add_u64 v[210:211], s[40:41], 0, v[196:197]
	s_mov_b32 m0, s42
	s_nop 0
	global_load_lds_dwordx4 v[210:211], off
	v_lshl_add_u64 v[210:211], s[40:41], 0, v[32:33]
	s_add_i32 m0, s42, 0x2000
	s_nop 0
	global_load_lds_dwordx4 v[210:211], off
	v_lshl_add_u64 v[210:211], v[214:215], 0, s[36:37]
	s_mov_b32 m0, s56
	s_nop 0
	global_load_lds_dwordx4 v[210:211], off
	v_lshl_add_u64 v[210:211], v[216:217], 0, s[36:37]
	s_mov_b32 m0, s57
	s_nop 0
	global_load_lds_dwordx4 v[210:211], off
	s_waitcnt vmcnt(8)
	s_waitcnt lgkmcnt(0)
	v_mfma_f32_16x16x32_bf16 v[64:67], v[132:135], v[164:167], v[64:67]
	v_mfma_f32_16x16x32_bf16 v[60:63], v[140:143], v[164:167], v[60:63]
	v_mfma_f32_16x16x32_bf16 v[52:55], v[132:135], v[172:175], v[52:55]
	v_mfma_f32_16x16x32_bf16 v[44:47], v[140:143], v[172:175], v[44:47]
	s_barrier
	s_setprio 1
	v_mfma_f32_16x16x32_bf16 v[36:39], v[132:135], v[180:183], v[36:39]
	v_mfma_f32_16x16x32_bf16 v[24:27], v[140:143], v[180:183], v[24:27]
	v_mfma_f32_16x16x32_bf16 v[16:19], v[132:135], v[188:191], v[16:19]
	v_mfma_f32_16x16x32_bf16 v[8:11], v[140:143], v[188:191], v[8:11]
	v_mfma_f32_16x16x32_bf16 v[64:67], v[136:139], v[168:171], v[64:67]
	v_mfma_f32_16x16x32_bf16 v[60:63], v[144:147], v[168:171], v[60:63]
	v_mfma_f32_16x16x32_bf16 v[52:55], v[136:139], v[176:179], v[52:55]
	v_mfma_f32_16x16x32_bf16 v[44:47], v[144:147], v[176:179], v[44:47]
	v_mfma_f32_16x16x32_bf16 v[36:39], v[136:139], v[184:187], v[36:39]
	v_mfma_f32_16x16x32_bf16 v[24:27], v[144:147], v[184:187], v[24:27]
	v_mfma_f32_16x16x32_bf16 v[16:19], v[136:139], v[192:195], v[16:19]
	v_mfma_f32_16x16x32_bf16 v[8:11], v[144:147], v[192:195], v[8:11]
	s_setprio 0
	s_setprio 1
	v_mfma_f32_16x16x32_bf16 v[56:59], v[148:151], v[164:167], v[56:59]
	v_mfma_f32_16x16x32_bf16 v[48:51], v[156:159], v[164:167], v[48:51]
	v_mfma_f32_16x16x32_bf16 v[40:43], v[148:151], v[172:175], v[40:43]
	v_mfma_f32_16x16x32_bf16 v[28:31], v[156:159], v[172:175], v[28:31]
	v_mfma_f32_16x16x32_bf16 v[20:23], v[148:151], v[180:183], v[20:23]
	v_mfma_f32_16x16x32_bf16 v[12:15], v[156:159], v[180:183], v[12:15]
	v_mfma_f32_16x16x32_bf16 v[4:7], v[148:151], v[188:191], v[4:7]
	v_mfma_f32_16x16x32_bf16 v[0:3], v[156:159], v[188:191], v[0:3]
	v_mfma_f32_16x16x32_bf16 v[56:59], v[152:155], v[168:171], v[56:59]
	v_mfma_f32_16x16x32_bf16 v[48:51], v[160:163], v[168:171], v[48:51]
	v_mfma_f32_16x16x32_bf16 v[40:43], v[152:155], v[176:179], v[40:43]
	v_mfma_f32_16x16x32_bf16 v[28:31], v[160:163], v[176:179], v[28:31]
	v_mfma_f32_16x16x32_bf16 v[20:23], v[152:155], v[184:187], v[20:23]
	v_mfma_f32_16x16x32_bf16 v[12:15], v[160:163], v[184:187], v[12:15]
	v_mfma_f32_16x16x32_bf16 v[4:7], v[152:155], v[192:195], v[4:7]
	v_mfma_f32_16x16x32_bf16 v[0:3], v[160:163], v[192:195], v[0:3]
	s_setprio 0
	s_barrier
	s_add_i32 s64, s64, 2
	s_add_u32 s0, s0, 0x100
	s_addc_u32 s1, s1, 0
	s_add_u32 s62, s62, 0x100
	s_addc_u32 s63, s63, 0
	s_cmp_gt_u32 s64, 5
	s_cbranch_scc1 .Lkexit_br
	s_cmp_eq_u32 s64, 4
	s_cbranch_scc0 .LBB0_49
	s_cmp_lg_u64 s[38:39], 0
	s_cbranch_scc1 .LBB0_49
.Ltail_br:
	s_add_u32 s40, s0, 0xfffe0080
	s_addc_u32 s41, s1, -1
	s_add_i32 s65, 0, 0x10000
	s_cmp_eq_u32 s64, 4
	s_cselect_b32 s43, s19, s41
	s_cselect_b32 s42, s60, s40
	s_cselect_b32 s41, s17, s63
	s_cselect_b32 s40, s61, s62
	s_add_i32 s68, 0, 0x14000
	v_add_u32_e32 v144, s65, v248
	v_add_u32_e32 v160, s68, v248
	ds_read_b128 v[132:135], v144
	ds_read_b128 v[136:139], v144 offset:1024
	ds_read_b128 v[140:143], v144 offset:2048
	ds_read_b128 v[144:147], v144 offset:3072
	ds_read_b128 v[148:151], v160
	ds_read_b128 v[152:155], v160 offset:1024
	ds_read_b128 v[156:159], v160 offset:2048
	ds_read_b128 v[160:163], v160 offset:3072
	v_lshl_add_u64 v[210:211], s[0:1], 0, v[206:207]
	s_add_i32 m0, s51, 0xc000
	ds_read_b128 v[164:167], v250
	ds_read_b128 v[168:171], v250 offset:1024
	ds_read_b128 v[172:175], v250 offset:2048
	ds_read_b128 v[176:179], v250 offset:3072
	ds_read_b128 v[180:183], v250 offset:4096
	ds_read_b128 v[184:187], v250 offset:5120
	ds_read_b128 v[188:191], v250 offset:6144
	ds_read_b128 v[192:195], v250 offset:7168
	global_load_lds_dwordx4 v[210:211], off
	v_lshl_add_u64 v[210:211], s[0:1], 0, v[208:209]
	s_add_i32 m0, s51, 0xe000
	s_nop 0
	global_load_lds_dwordx4 v[210:211], off
	s_waitcnt vmcnt(8)
	s_waitcnt lgkmcnt(0)
	v_mfma_f32_16x16x32_bf16 v[128:131], v[132:135], v[164:167], v[128:131]
	v_mfma_f32_16x16x32_bf16 v[124:127], v[140:143], v[164:167], v[124:127]
	v_mfma_f32_16x16x32_bf16 v[116:119], v[132:135], v[172:175], v[116:119]
	v_mfma_f32_16x16x32_bf16 v[108:111], v[140:143], v[172:175], v[108:111]
	s_barrier
; #define PG8_STAGE(bufoff, gbase, voff) do { _Pragma("unroll") for (int _i = 0; _i < 2; ++_i) \
;         __builtin_amdgcn_global_load_lds((const unsigned*)((const char*)(gbase) + (voff)[_i]), (PG8_LAS unsigned*)(lds + (bufoff) + ldsw + _i * 8192), 16, 0, 0); } while (0)
; #define PG8_LDA(dst, b, h) do { _Pragma("unroll") for (int m = 0; m < 4; ++m) _Pragma("unroll") for (int k = 0; k < 2; ++k) dst[m][k] = *(const PG8_LAS bf16x8*)(lds + PG8_SA(b, h) + aoff + m * 2048 + k * 1024); } while (0)
; #define PG8_MMA(ai, bj, At, Bt) do { __builtin_amdgcn_s_setprio(1); _Pragma("unroll") for (int m = 0; m < 4; ++m) _Pragma("unroll") for (int n = 0; n < 2; ++n) _Pragma("unroll") for (int k = 0; k < 2; ++k) \
;         acc[ai][bj][m][n] = __builtin_amdgcn_mfma_f32_16x16x32_bf16(Bt[n][k], At[m][k], acc[ai][bj][m][n], 0, 0, 0); __builtin_amdgcn_s_setprio(0); } while (0)
; #define PG8_WAIT_V(n) asm volatile("s_waitcnt vmcnt(" #n ")" ::: "memory")
; #define PG8_WAIT_L(n) asm volatile("s_waitcnt lgkmcnt(" #n ")" ::: "memory")
; #define PG8_BAR __builtin_amdgcn_s_barrier()
; #define PG8_SCHED __builtin_amdgcn_sched_barrier(0)
; template <class Epi, class Sched, bool ALIGN_EPI = false, bool SP2 = false>
; __device__ __forceinline__ void gemm_phase(PG8_LAS unsigned char* lds, const Gemm g, const Sched& S, const Epi& E) {
;     ...
;             PG8_WAIT_V(8); PG8_WAIT_L(0); PG8_BAR; PG8_MMA(0, 0, At, B0); PG8_MMA(0, 1, At, B1); PG8_BAR; PG8_SCHED;
;             PG8_LDA(At, 0, 1); PG8_STAGE(PG8_SB(0, 0), b2, voffB); PG8_STAGE(PG8_SB(0, 1), b2 + hstep, voffB); PG8_STAGE(PG8_SA(0, 0), a2, voffA);
;             PG8_WAIT_V(8); PG8_WAIT_L(0); PG8_BAR; PG8_MMA(1, 0, At, B0); PG8_MMA(1, 1, At, B1); PG8_BAR; PG8_SCHED;
	s_setprio 1
	v_mfma_f32_16x16x32_bf16 v[100:103], v[132:135], v[180:183], v[100:103]
	v_mfma_f32_16x16x32_bf16 v[92:95], v[140:143], v[180:183], v[92:95]
	v_mfma_f32_16x16x32_bf16 v[84:87], v[132:135], v[188:191], v[84:87]
	v_mfma_f32_16x16x32_bf16 v[76:79], v[140:143], v[188:191], v[76:79]
	v_mfma_f32_16x16x32_bf16 v[128:131], v[136:139], v[168:171], v[128:131]
	v_mfma_f32_16x16x32_bf16 v[124:127], v[144:147], v[168:171], v[124:127]
	v_mfma_f32_16x16x32_bf16 v[116:119], v[136:139], v[176:179], v[116:119]
	v_mfma_f32_16x16x32_bf16 v[108:111], v[144:147], v[176:179], v[108:111]
	v_mfma_f32_16x16x32_bf16 v[100:103], v[136:139], v[184:187], v[100:103]
	v_mfma_f32_16x16x32_bf16 v[92:95], v[144:147], v[184:187], v[92:95]
	v_mfma_f32_16x16x32_bf16 v[84:87], v[136:139], v[192:195], v[84:87]
	v_mfma_f32_16x16x32_bf16 v[76:79], v[144:147], v[192:195], v[76:79]
	s_setprio 0
	s_setprio 1
	v_mfma_f32_16x16x32_bf16 v[120:123], v[148:151], v[164:167], v[120:123]
	v_mfma_f32_16x16x32_bf16 v[112:115], v[156:159], v[164:167], v[112:115]
	v_mfma_f32_16x16x32_bf16 v[104:107], v[148:151], v[172:175], v[104:107]
	v_mfma_f32_16x16x32_bf16 v[96:99], v[156:159], v[172:175], v[96:99]
	v_mfma_f32_16x16x32_bf16 v[88:91], v[148:151], v[180:183], v[88:91]
	v_mfma_f32_16x16x32_bf16 v[80:83], v[156:159], v[180:183], v[80:83]
	v_mfma_f32_16x16x32_bf16 v[72:75], v[148:151], v[188:191], v[72:75]
	v_mfma_f32_16x16x32_bf16 v[68:71], v[156:159], v[188:191], v[68:71]
	v_mfma_f32_16x16x32_bf16 v[120:123], v[152:155], v[168:171], v[120:123]
	v_mfma_f32_16x16x32_bf16 v[112:115], v[160:163], v[168:171], v[112:115]
	v_mfma_f32_16x16x32_bf16 v[104:107], v[152:155], v[176:179], v[104:107]
	v_mfma_f32_16x16x32_bf16 v[96:99], v[160:163], v[176:179], v[96:99]
	v_mfma_f32_16x16x32_bf16 v[88:91], v[152:155], v[184:187], v[88:91]
	v_mfma_f32_16x16x32_bf16 v[80:83], v[160:163], v[184:187], v[80:83]
	v_mfma_f32_16x16x32_bf16 v[72:75], v[152:155], v[192:195], v[72:75]
	v_mfma_f32_16x16x32_bf16 v[68:71], v[160:163], v[192:195], v[68:71]
	s_setprio 0
	s_barrier
	s_add_i32 s65, s65, s50
	v_lshl_add_u64 v[210:211], s[40:41], 0, v[196:197]
	s_mov_b32 m0, s65
	ds_read_b128 v[164:167], v250 offset:16384
	ds_read_b128 v[168:171], v250 offset:17408
	ds_read_b128 v[172:175], v250 offset:18432
	ds_read_b128 v[176:179], v250 offset:19456
	ds_read_b128 v[180:183], v250 offset:20480
	ds_read_b128 v[184:187], v250 offset:21504
	ds_read_b128 v[188:191], v250 offset:22528
	ds_read_b128 v[192:195], v250 offset:23552
	s_add_i32 m0, s65, 0x2000
	s_add_u32 s66, s40, 0x20000
	v_lshl_add_u64 v[212:213], s[40:41], 0, v[32:33]
	s_addc_u32 s67, s41, 0
	s_add_i32 s65, s68, s50
	v_lshl_add_u64 v[214:215], s[66:67], 0, v[196:197]
	s_mov_b32 m0, s65
	v_lshl_add_u64 v[216:217], s[42:43], 0, v[202:203]
	v_lshl_add_u64 v[214:215], s[66:67], 0, v[32:33]
	s_add_i32 m0, s65, 0x2000
	s_nop 0
	v_lshl_add_u64 v[214:215], s[42:43], 0, v[204:205]
	s_mov_b32 m0, s51
	s_nop 0
	s_mov_b32 m0, s52
	s_nop 0
	s_waitcnt vmcnt(2)
	s_waitcnt lgkmcnt(0)
	v_mfma_f32_16x16x32_bf16 v[64:67], v[132:135], v[164:167], v[64:67]
	v_mfma_f32_16x16x32_bf16 v[60:63], v[140:143], v[164:167], v[60:63]
	v_mfma_f32_16x16x32_bf16 v[52:55], v[132:135], v[172:175], v[52:55]
	v_mfma_f32_16x16x32_bf16 v[44:47], v[140:143], v[172:175], v[44:47]
	s_barrier
	s_setprio 1
	v_mfma_f32_16x16x32_bf16 v[36:39], v[132:135], v[180:183], v[36:39]
	v_mfma_f32_16x16x32_bf16 v[24:27], v[140:143], v[180:183], v[24:27]
	v_mfma_f32_16x16x32_bf16 v[16:19], v[132:135], v[188:191], v[16:19]
	v_mfma_f32_16x16x32_bf16 v[8:11], v[140:143], v[188:191], v[8:11]
	v_mfma_f32_16x16x32_bf16 v[64:67], v[136:139], v[168:171], v[64:67]
	v_mfma_f32_16x16x32_bf16 v[60:63], v[144:147], v[168:171], v[60:63]
	v_mfma_f32_16x16x32_bf16 v[52:55], v[136:139], v[176:179], v[52:55]
	v_mfma_f32_16x16x32_bf16 v[44:47], v[144:147], v[176:179], v[44:47]
	v_mfma_f32_16x16x32_bf16 v[36:39], v[136:139], v[184:187], v[36:39]
	v_mfma_f32_16x16x32_bf16 v[24:27], v[144:147], v[184:187], v[24:27]
	v_mfma_f32_16x16x32_bf16 v[16:19], v[136:139], v[192:195], v[16:19]
	v_mfma_f32_16x16x32_bf16 v[8:11], v[144:147], v[192:195], v[8:11]
	s_setprio 0
	s_setprio 1
	v_mfma_f32_16x16x32_bf16 v[56:59], v[148:151], v[164:167], v[56:59]
	v_mfma_f32_16x16x32_bf16 v[48:51], v[156:159], v[164:167], v[48:51]
	v_mfma_f32_16x16x32_bf16 v[40:43], v[148:151], v[172:175], v[40:43]
	v_mfma_f32_16x16x32_bf16 v[28:31], v[156:159], v[172:175], v[28:31]
	v_mfma_f32_16x16x32_bf16 v[20:23], v[148:151], v[180:183], v[20:23]
	v_mfma_f32_16x16x32_bf16 v[12:15], v[156:159], v[180:183], v[12:15]
	v_mfma_f32_16x16x32_bf16 v[4:7], v[148:151], v[188:191], v[4:7]
	v_mfma_f32_16x16x32_bf16 v[0:3], v[156:159], v[188:191], v[0:3]
	v_mfma_f32_16x16x32_bf16 v[56:59], v[152:155], v[168:171], v[56:59]
	v_mfma_f32_16x16x32_bf16 v[48:51], v[160:163], v[168:171], v[48:51]
	v_mfma_f32_16x16x32_bf16 v[40:43], v[152:155], v[176:179], v[40:43]
	v_mfma_f32_16x16x32_bf16 v[28:31], v[160:163], v[176:179], v[28:31]
	v_mfma_f32_16x16x32_bf16 v[20:23], v[152:155], v[184:187], v[20:23]
	v_mfma_f32_16x16x32_bf16 v[12:15], v[160:163], v[184:187], v[12:15]
	v_mfma_f32_16x16x32_bf16 v[4:7], v[152:155], v[192:195], v[4:7]
	v_mfma_f32_16x16x32_bf16 v[0:3], v[160:163], v[192:195], v[0:3]
	s_setprio 0
	s_barrier
; #define PG8_STAGE(bufoff, gbase, voff) do { _Pragma("unroll") for (int _i = 0; _i < 2; ++_i) \
;         __builtin_amdgcn_global_load_lds((const unsigned*)((const char*)(gbase) + (voff)[_i]), (PG8_LAS unsigned*)(lds + (bufoff) + ldsw + _i * 8192), 16, 0, 0); } while (0)
; #define PG8_LDA(dst, b, h) do { _Pragma("unroll") for (int m = 0; m < 4; ++m) _Pragma("unroll") for (int k = 0; k < 2; ++k) dst[m][k] = *(const PG8_LAS bf16x8*)(lds + PG8_SA(b, h) + aoff + m * 2048 + k * 1024); } while (0)
; #define PG8_LDB(dst, b, h) do { _Pragma("unroll") for (int n = 0; n < 2; ++n) _Pragma("unroll") for (int k = 0; k < 2; ++k) dst[n][k] = *(const PG8_LAS bf16x8*)(lds + PG8_SB(b, h) + boff + n * 2048 + k * 1024); } while (0)
; #define PG8_MMA(ai, bj, At, Bt) do { __builtin_amdgcn_s_setprio(1); _Pragma("unroll") for (int m = 0; m < 4; ++m) _Pragma("unroll") for (int n = 0; n < 2; ++n) _Pragma("unroll") for (int k = 0; k < 2; ++k) \
;         acc[ai][bj][m][n] = __builtin_amdgcn_mfma_f32_16x16x32_bf16(Bt[n][k], At[m][k], acc[ai][bj][m][n], 0, 0, 0); __builtin_amdgcn_s_setprio(0); } while (0)
; #define PG8_WAIT_V(n) asm volatile("s_waitcnt vmcnt(" #n ")" ::: "memory")
; #define PG8_WAIT_L(n) asm volatile("s_waitcnt lgkmcnt(" #n ")" ::: "memory")
; #define PG8_BAR __builtin_amdgcn_s_barrier()
; #define PG8_SCHED __builtin_amdgcn_sched_barrier(0)
; template <class Epi, class Sched, bool ALIGN_EPI = false, bool SP2 = false>
; __device__ __forceinline__ void gemm_phase(PG8_LAS unsigned char* lds, const Gemm g, const Sched& S, const Epi& E) {
;     ...
;             PG8_LDB(B0, 1, 0); PG8_LDB(B1, 1, 1); PG8_SCHED; PG8_LDA(At, 1, 0); PG8_STAGE(PG8_SA(0, 1), a2 + hstep, voffA);
;             PG8_WAIT_V(8); PG8_WAIT_L(0); PG8_BAR; PG8_MMA(0, 0, At, B0); PG8_MMA(0, 1, At, B1); PG8_BAR; PG8_SCHED;
;             PG8_LDA(At, 1, 1); PG8_STAGE(PG8_SB(1, 0), b3, voffB); PG8_STAGE(PG8_SB(1, 1), b3 + hstep, voffB); PG8_STAGE(PG8_SA(1, 0), a3, voffA);
;             PG8_WAIT_V(8); PG8_WAIT_L(0); PG8_BAR; PG8_MMA(1, 0, At, B0); PG8_MMA(1, 1, At, B1); PG8_BAR; PG8_SCHED;
;     ...
;         if constexpr (ALIGN_EPI) { if (wr == 0) PG8_BAR; }
	s_add_i32 s65, 0, 0x18000
	s_add_i32 s66, 0, 0x1c000
	v_add_u32_e32 v144, s65, v248
	v_add_u32_e32 v160, s66, v248
	ds_read_b128 v[132:135], v144
	ds_read_b128 v[136:139], v144 offset:1024
	ds_read_b128 v[140:143], v144 offset:2048
	ds_read_b128 v[144:147], v144 offset:3072
	ds_read_b128 v[148:151], v160
	ds_read_b128 v[152:155], v160 offset:1024
	ds_read_b128 v[156:159], v160 offset:2048
	ds_read_b128 v[160:163], v160 offset:3072
	s_add_u32 s42, s42, 0x20000
	s_addc_u32 s43, s43, 0
	s_mov_b32 m0, s53
	v_lshl_add_u64 v[218:219], s[42:43], 0, v[204:205]
	ds_read_b128 v[164:167], v250 offset:32768
	ds_read_b128 v[168:171], v250 offset:33792
	ds_read_b128 v[172:175], v250 offset:34816
	ds_read_b128 v[176:179], v250 offset:35840
	ds_read_b128 v[180:183], v250 offset:36864
	ds_read_b128 v[184:187], v250 offset:37888
	ds_read_b128 v[188:191], v250 offset:38912
	ds_read_b128 v[192:195], v250 offset:39936
	v_lshl_add_u64 v[218:219], s[42:43], 0, v[202:203]
	s_mov_b32 m0, s54
	s_nop 0
	s_waitcnt vmcnt(0)
	s_waitcnt lgkmcnt(0)
	v_mfma_f32_16x16x32_bf16 v[128:131], v[132:135], v[164:167], v[128:131]
	v_mfma_f32_16x16x32_bf16 v[124:127], v[140:143], v[164:167], v[124:127]
	v_mfma_f32_16x16x32_bf16 v[116:119], v[132:135], v[172:175], v[116:119]
	v_mfma_f32_16x16x32_bf16 v[108:111], v[140:143], v[172:175], v[108:111]
	s_barrier
	s_setprio 1
	v_mfma_f32_16x16x32_bf16 v[100:103], v[132:135], v[180:183], v[100:103]
	v_mfma_f32_16x16x32_bf16 v[92:95], v[140:143], v[180:183], v[92:95]
	v_mfma_f32_16x16x32_bf16 v[84:87], v[132:135], v[188:191], v[84:87]
	v_mfma_f32_16x16x32_bf16 v[76:79], v[140:143], v[188:191], v[76:79]
	v_mfma_f32_16x16x32_bf16 v[128:131], v[136:139], v[168:171], v[128:131]
	v_mfma_f32_16x16x32_bf16 v[124:127], v[144:147], v[168:171], v[124:127]
	v_mfma_f32_16x16x32_bf16 v[116:119], v[136:139], v[176:179], v[116:119]
	v_mfma_f32_16x16x32_bf16 v[108:111], v[144:147], v[176:179], v[108:111]
	v_mfma_f32_16x16x32_bf16 v[100:103], v[136:139], v[184:187], v[100:103]
	v_mfma_f32_16x16x32_bf16 v[92:95], v[144:147], v[184:187], v[92:95]
	v_mfma_f32_16x16x32_bf16 v[84:87], v[136:139], v[192:195], v[84:87]
	v_mfma_f32_16x16x32_bf16 v[76:79], v[144:147], v[192:195], v[76:79]
	s_setprio 0
	s_setprio 1
	v_mfma_f32_16x16x32_bf16 v[120:123], v[148:151], v[164:167], v[120:123]
	v_mfma_f32_16x16x32_bf16 v[112:115], v[156:159], v[164:167], v[112:115]
	v_mfma_f32_16x16x32_bf16 v[104:107], v[148:151], v[172:175], v[104:107]
	v_mfma_f32_16x16x32_bf16 v[96:99], v[156:159], v[172:175], v[96:99]
	v_mfma_f32_16x16x32_bf16 v[88:91], v[148:151], v[180:183], v[88:91]
	v_mfma_f32_16x16x32_bf16 v[80:83], v[156:159], v[180:183], v[80:83]
	v_mfma_f32_16x16x32_bf16 v[72:75], v[148:151], v[188:191], v[72:75]
	v_mfma_f32_16x16x32_bf16 v[68:71], v[156:159], v[188:191], v[68:71]
	v_mfma_f32_16x16x32_bf16 v[120:123], v[152:155], v[168:171], v[120:123]
	v_mfma_f32_16x16x32_bf16 v[112:115], v[160:163], v[168:171], v[112:115]
	v_mfma_f32_16x16x32_bf16 v[104:107], v[152:155], v[176:179], v[104:107]
	v_mfma_f32_16x16x32_bf16 v[96:99], v[160:163], v[176:179], v[96:99]
	v_mfma_f32_16x16x32_bf16 v[88:91], v[152:155], v[184:187], v[88:91]
	v_mfma_f32_16x16x32_bf16 v[80:83], v[160:163], v[184:187], v[80:83]
	v_mfma_f32_16x16x32_bf16 v[72:75], v[152:155], v[192:195], v[72:75]
	v_mfma_f32_16x16x32_bf16 v[68:71], v[160:163], v[192:195], v[68:71]
	s_setprio 0
	s_barrier
	s_add_i32 s42, s65, s50
	v_lshl_add_u64 v[210:211], v[210:211], 0, s[36:37]
	s_mov_b32 m0, s42
	ds_read_b128 v[164:167], v250 offset:49152
	ds_read_b128 v[168:171], v250 offset:50176
	ds_read_b128 v[172:175], v250 offset:51200
	ds_read_b128 v[176:179], v250 offset:52224
	ds_read_b128 v[180:183], v250 offset:53248
	ds_read_b128 v[184:187], v250 offset:54272
	ds_read_b128 v[188:191], v250 offset:55296
	ds_read_b128 v[192:195], v250 offset:56320
	s_add_i32 m0, s42, 0x2000
	s_add_u32 s40, s40, 0x20080
	v_lshl_add_u64 v[210:211], v[212:213], 0, s[36:37]
	s_addc_u32 s41, s41, 0
	s_add_i32 s42, s66, s50
	v_lshl_add_u64 v[210:211], s[40:41], 0, v[196:197]
	s_mov_b32 m0, s42
	s_nop 0
	v_lshl_add_u64 v[210:211], s[40:41], 0, v[32:33]
	s_add_i32 m0, s42, 0x2000
	s_nop 0
	v_lshl_add_u64 v[210:211], v[214:215], 0, s[36:37]
	s_mov_b32 m0, s56
	s_nop 0
	v_lshl_add_u64 v[210:211], v[216:217], 0, s[36:37]
	s_mov_b32 m0, s57
	s_nop 0
	s_waitcnt vmcnt(0)
	s_waitcnt lgkmcnt(0)
	v_mfma_f32_16x16x32_bf16 v[64:67], v[132:135], v[164:167], v[64:67]
	v_mfma_f32_16x16x32_bf16 v[60:63], v[140:143], v[164:167], v[60:63]
	v_mfma_f32_16x16x32_bf16 v[52:55], v[132:135], v[172:175], v[52:55]
	v_mfma_f32_16x16x32_bf16 v[44:47], v[140:143], v[172:175], v[44:47]
	s_barrier
	s_setprio 1
	v_mfma_f32_16x16x32_bf16 v[36:39], v[132:135], v[180:183], v[36:39]
	v_mfma_f32_16x16x32_bf16 v[24:27], v[140:143], v[180:183], v[24:27]
	v_mfma_f32_16x16x32_bf16 v[16:19], v[132:135], v[188:191], v[16:19]
	v_mfma_f32_16x16x32_bf16 v[8:11], v[140:143], v[188:191], v[8:11]
	v_mfma_f32_16x16x32_bf16 v[64:67], v[136:139], v[168:171], v[64:67]
	v_mfma_f32_16x16x32_bf16 v[60:63], v[144:147], v[168:171], v[60:63]
	v_mfma_f32_16x16x32_bf16 v[52:55], v[136:139], v[176:179], v[52:55]
	v_mfma_f32_16x16x32_bf16 v[44:47], v[144:147], v[176:179], v[44:47]
	v_mfma_f32_16x16x32_bf16 v[36:39], v[136:139], v[184:187], v[36:39]
	v_mfma_f32_16x16x32_bf16 v[24:27], v[144:147], v[184:187], v[24:27]
	v_mfma_f32_16x16x32_bf16 v[16:19], v[136:139], v[192:195], v[16:19]
	v_mfma_f32_16x16x32_bf16 v[8:11], v[144:147], v[192:195], v[8:11]
	s_setprio 0
	s_setprio 1
	v_mfma_f32_16x16x32_bf16 v[56:59], v[148:151], v[164:167], v[56:59]
	v_mfma_f32_16x16x32_bf16 v[48:51], v[156:159], v[164:167], v[48:51]
	v_mfma_f32_16x16x32_bf16 v[40:43], v[148:151], v[172:175], v[40:43]
	v_mfma_f32_16x16x32_bf16 v[28:31], v[156:159], v[172:175], v[28:31]
	v_mfma_f32_16x16x32_bf16 v[20:23], v[148:151], v[180:183], v[20:23]
	v_mfma_f32_16x16x32_bf16 v[12:15], v[156:159], v[180:183], v[12:15]
	v_mfma_f32_16x16x32_bf16 v[4:7], v[148:151], v[188:191], v[4:7]
	v_mfma_f32_16x16x32_bf16 v[0:3], v[156:159], v[188:191], v[0:3]
	v_mfma_f32_16x16x32_bf16 v[56:59], v[152:155], v[168:171], v[56:59]
	v_mfma_f32_16x16x32_bf16 v[48:51], v[160:163], v[168:171], v[48:51]
	v_mfma_f32_16x16x32_bf16 v[40:43], v[152:155], v[176:179], v[40:43]
	v_mfma_f32_16x16x32_bf16 v[28:31], v[160:163], v[176:179], v[28:31]
	v_mfma_f32_16x16x32_bf16 v[20:23], v[152:155], v[184:187], v[20:23]
	v_mfma_f32_16x16x32_bf16 v[12:15], v[160:163], v[184:187], v[12:15]
	v_mfma_f32_16x16x32_bf16 v[4:7], v[152:155], v[192:195], v[4:7]
	v_mfma_f32_16x16x32_bf16 v[0:3], v[160:163], v[192:195], v[0:3]
	s_setprio 0
	s_barrier
	s_add_i32 s64, s64, 2
	s_add_u32 s0, s0, 0x100
	s_addc_u32 s1, s1, 0
	s_add_u32 s62, s62, 0x100
	s_addc_u32 s63, s63, 0
.Lkexit_br:
	s_and_b64 vcc, exec, s[12:13]
	s_cbranch_vccz .LBB0_52
	s_barrier

; #define PG8_STAGE(bufoff, gbase, voff) do { _Pragma("unroll") for (int _i = 0; _i < 2; ++_i) \
;         __builtin_amdgcn_global_load_lds((const unsigned*)((const char*)(gbase) + (voff)[_i]), (PG8_LAS unsigned*)(lds + (bufoff) + ldsw + _i * 8192), 16, 0, 0); } while (0)
; #define PG8_LDA(dst, b, h) do { _Pragma("unroll") for (int m = 0; m < 4; ++m) _Pragma("unroll") for (int k = 0; k < 2; ++k) dst[m][k] = *(const PG8_LAS bf16x8*)(lds + PG8_SA(b, h) + aoff + m * 2048 + k * 1024); } while (0)
; #define PG8_LDB(dst, b, h) do { _Pragma("unroll") for (int n = 0; n < 2; ++n) _Pragma("unroll") for (int k = 0; k < 2; ++k) dst[n][k] = *(const PG8_LAS bf16x8*)(lds + PG8_SB(b, h) + boff + n * 2048 + k * 1024); } while (0)
; #define PG8_MMA(ai, bj, At, Bt) do { __builtin_amdgcn_s_setprio(1); _Pragma("unroll") for (int m = 0; m < 4; ++m) _Pragma("unroll") for (int n = 0; n < 2; ++n) _Pragma("unroll") for (int k = 0; k < 2; ++k) \
;         acc[ai][bj][m][n] = __builtin_amdgcn_mfma_f32_16x16x32_bf16(Bt[n][k], At[m][k], acc[ai][bj][m][n], 0, 0, 0); __builtin_amdgcn_s_setprio(0); } while (0)
; #define PG8_WAIT_V(n) asm volatile("s_waitcnt vmcnt(" #n ")" ::: "memory")
; #define PG8_WAIT_L(n) asm volatile("s_waitcnt lgkmcnt(" #n ")" ::: "memory")
; template <class Epi, class Sched, bool ALIGN_EPI = false, bool SP2 = false>
; __device__ __forceinline__ void gemm_phase(PG8_LAS unsigned char* lds, const Gemm g, const Sched& S, const Epi& E) {
;     ...
;             const bool last = (t == nt - 2);
;             const char* a1 = cA + (size_t)(t + 1) * kstep;
;             const char* a2 = last ? nA : cA + (size_t)(t + 2) * kstep; const char* b2 = last ? nB : cB + (size_t)(t + 2) * kstep;
;             const char* a3 = a2 + kstep; const char* b3 = b2 + kstep;
;             if (last && has_next) S.a_ready(nxt);
;             if constexpr (SP2) {
;             PG8_LDB(B0, 0, 0); PG8_LDB(B1, 0, 1); PG8_SCHED; PG8_LDA(At, 0, 0); PG8_STAGE(PG8_SA(1, 1), a1 + hstep, voffA);
;             PG8_WAIT_V(8); PG8_WAIT_L(0); PG8_BAR; PG8_MMA(0, 0, At, B0); PG8_MMA(0, 1, At, B1); PG8_BAR; PG8_SCHED;
;             PG8_LDA(At, 0, 1); PG8_STAGE(PG8_SB(0, 0), b2, voffB); PG8_STAGE(PG8_SB(0, 1), b2 + hstep, voffB); PG8_STAGE(PG8_SA(0, 0), a2, voffA);
;             PG8_WAIT_V(8); PG8_WAIT_L(0); PG8_BAR; PG8_MMA(1, 0, At, B0); PG8_MMA(1, 1, At, B1); PG8_BAR; PG8_SCHED;
.LBB0_342:
	s_add_u32 s4, s0, 0xfffc0080
	s_addc_u32 s5, s1, -1
	s_add_i32 s60, 0, 0x10000
	s_cmp_eq_u32 s59, 12
	s_cselect_b32 s43, s21, s5
	s_cselect_b32 s42, s45, s4
	s_cselect_b32 s5, s19, s58
	s_cselect_b32 s4, s46, s47
	s_add_i32 s62, 0, 0x14000
	v_add_u32_e32 v144, s60, v170
	v_add_u32_e32 v174, s62, v170
	ds_read_b128 v[132:135], v144
	ds_read_b128 v[136:139], v144 offset:1024
	ds_read_b128 v[140:143], v144 offset:2048
	ds_read_b128 v[144:147], v144 offset:3072
	ds_read_b128 v[158:161], v174
	ds_read_b128 v[162:165], v174 offset:1024
	ds_read_b128 v[166:169], v174 offset:2048
	ds_read_b128 v[174:177], v174 offset:3072
	v_lshl_add_u64 v[194:195], s[0:1], 0, v[154:155]
	s_add_i32 m0, s50, 0xc000
	ds_read_b128 v[178:181], v173
	ds_read_b128 v[182:185], v173 offset:1024
	ds_read_b128 v[186:189], v173 offset:2048
	ds_read_b128 v[190:193], v173 offset:3072
	ds_read_b128 v[202:205], v173 offset:4096
	ds_read_b128 v[206:209], v173 offset:5120
	ds_read_b128 v[210:213], v173 offset:6144
	ds_read_b128 v[214:217], v173 offset:7168
	global_load_lds_dwordx4 v[194:195], off
	v_lshl_add_u64 v[194:195], s[0:1], 0, v[156:157]
	s_add_i32 m0, s50, 0xe000
	s_nop 0
	global_load_lds_dwordx4 v[194:195], off
	s_waitcnt vmcnt(8)
	s_waitcnt lgkmcnt(0)
	v_mfma_f32_16x16x32_bf16 v[128:131], v[132:135], v[178:181], v[128:131]
	v_mfma_f32_16x16x32_bf16 v[124:127], v[140:143], v[178:181], v[124:127]
	v_mfma_f32_16x16x32_bf16 v[112:115], v[132:135], v[186:189], v[112:115]
	v_mfma_f32_16x16x32_bf16 v[108:111], v[140:143], v[186:189], v[108:111]
	s_barrier
	s_setprio 1
	v_mfma_f32_16x16x32_bf16 v[96:99], v[132:135], v[202:205], v[96:99]
	v_mfma_f32_16x16x32_bf16 v[92:95], v[140:143], v[202:205], v[92:95]
	v_mfma_f32_16x16x32_bf16 v[80:83], v[132:135], v[210:213], v[80:83]
	v_mfma_f32_16x16x32_bf16 v[76:79], v[140:143], v[210:213], v[76:79]
	v_mfma_f32_16x16x32_bf16 v[128:131], v[136:139], v[182:185], v[128:131]
	v_mfma_f32_16x16x32_bf16 v[124:127], v[144:147], v[182:185], v[124:127]
	v_mfma_f32_16x16x32_bf16 v[112:115], v[136:139], v[190:193], v[112:115]
	v_mfma_f32_16x16x32_bf16 v[108:111], v[144:147], v[190:193], v[108:111]
	v_mfma_f32_16x16x32_bf16 v[96:99], v[136:139], v[206:209], v[96:99]
	v_mfma_f32_16x16x32_bf16 v[92:95], v[144:147], v[206:209], v[92:95]
	v_mfma_f32_16x16x32_bf16 v[80:83], v[136:139], v[214:217], v[80:83]
	v_mfma_f32_16x16x32_bf16 v[76:79], v[144:147], v[214:217], v[76:79]
	s_setprio 0
	s_setprio 1
	v_mfma_f32_16x16x32_bf16 v[120:123], v[158:161], v[178:181], v[120:123]
	v_mfma_f32_16x16x32_bf16 v[116:119], v[166:169], v[178:181], v[116:119]
	v_mfma_f32_16x16x32_bf16 v[104:107], v[158:161], v[186:189], v[104:107]
	v_mfma_f32_16x16x32_bf16 v[100:103], v[166:169], v[186:189], v[100:103]
	v_mfma_f32_16x16x32_bf16 v[88:91], v[158:161], v[202:205], v[88:91]
	v_mfma_f32_16x16x32_bf16 v[84:87], v[166:169], v[202:205], v[84:87]
	v_mfma_f32_16x16x32_bf16 v[72:75], v[158:161], v[210:213], v[72:75]
	v_mfma_f32_16x16x32_bf16 v[68:71], v[166:169], v[210:213], v[68:71]
	v_mfma_f32_16x16x32_bf16 v[120:123], v[162:165], v[182:185], v[120:123]
	v_mfma_f32_16x16x32_bf16 v[116:119], v[174:177], v[182:185], v[116:119]
	v_mfma_f32_16x16x32_bf16 v[104:107], v[162:165], v[190:193], v[104:107]
	v_mfma_f32_16x16x32_bf16 v[100:103], v[174:177], v[190:193], v[100:103]
	v_mfma_f32_16x16x32_bf16 v[88:91], v[162:165], v[206:209], v[88:91]
	v_mfma_f32_16x16x32_bf16 v[84:87], v[174:177], v[206:209], v[84:87]
	v_mfma_f32_16x16x32_bf16 v[72:75], v[162:165], v[214:217], v[72:75]
	v_mfma_f32_16x16x32_bf16 v[68:71], v[174:177], v[214:217], v[68:71]
	s_setprio 0
	s_barrier
	s_add_i32 s60, s60, s49
	v_lshl_add_u64 v[194:195], s[4:5], 0, v[150:151]
	s_mov_b32 m0, s60
	ds_read_b128 v[178:181], v173 offset:16384
	ds_read_b128 v[182:185], v173 offset:17408
	ds_read_b128 v[186:189], v173 offset:18432
	ds_read_b128 v[190:193], v173 offset:19456
	ds_read_b128 v[202:205], v173 offset:20480
	ds_read_b128 v[206:209], v173 offset:21504
	ds_read_b128 v[210:213], v173 offset:22528
	ds_read_b128 v[214:217], v173 offset:23552
	global_load_lds_dwordx4 v[194:195], off
	s_add_i32 m0, s60, 0x2000
	s_add_u32 s60, s4, 0x40000
	v_lshl_add_u64 v[218:219], s[4:5], 0, v[32:33]
	s_addc_u32 s61, s5, 0
	s_add_i32 s62, s62, s49
	global_load_lds_dwordx4 v[218:219], off
	v_lshl_add_u64 v[220:221], s[60:61], 0, v[150:151]
	s_mov_b32 m0, s62
	v_lshl_add_u64 v[222:223], s[42:43], 0, v[148:149]
	global_load_lds_dwordx4 v[220:221], off
	v_lshl_add_u64 v[220:221], s[60:61], 0, v[32:33]
	s_add_i32 m0, s62, 0x2000
	s_nop 0
	global_load_lds_dwordx4 v[220:221], off
	v_lshl_add_u64 v[220:221], s[42:43], 0, v[152:153]
	s_mov_b32 m0, s50
	s_nop 0
	global_load_lds_dwordx4 v[220:221], off
	s_mov_b32 m0, s51
	s_nop 0
	global_load_lds_dwordx4 v[222:223], off
	s_waitcnt vmcnt(8)
	s_waitcnt lgkmcnt(0)
	v_mfma_f32_16x16x32_bf16 v[64:67], v[132:135], v[178:181], v[64:67]
	v_mfma_f32_16x16x32_bf16 v[60:63], v[140:143], v[178:181], v[60:63]
	v_mfma_f32_16x16x32_bf16 v[48:51], v[132:135], v[186:189], v[48:51]
	v_mfma_f32_16x16x32_bf16 v[44:47], v[140:143], v[186:189], v[44:47]
	s_barrier
; #define PG8_STAGE(bufoff, gbase, voff) do { _Pragma("unroll") for (int _i = 0; _i < 2; ++_i) \
;         __builtin_amdgcn_global_load_lds((const unsigned*)((const char*)(gbase) + (voff)[_i]), (PG8_LAS unsigned*)(lds + (bufoff) + ldsw + _i * 8192), 16, 0, 0); } while (0)
; #define PG8_LDA(dst, b, h) do { _Pragma("unroll") for (int m = 0; m < 4; ++m) _Pragma("unroll") for (int k = 0; k < 2; ++k) dst[m][k] = *(const PG8_LAS bf16x8*)(lds + PG8_SA(b, h) + aoff + m * 2048 + k * 1024); } while (0)
; #define PG8_LDB(dst, b, h) do { _Pragma("unroll") for (int n = 0; n < 2; ++n) _Pragma("unroll") for (int k = 0; k < 2; ++k) dst[n][k] = *(const PG8_LAS bf16x8*)(lds + PG8_SB(b, h) + boff + n * 2048 + k * 1024); } while (0)
; #define PG8_MMA(ai, bj, At, Bt) do { __builtin_amdgcn_s_setprio(1); _Pragma("unroll") for (int m = 0; m < 4; ++m) _Pragma("unroll") for (int n = 0; n < 2; ++n) _Pragma("unroll") for (int k = 0; k < 2; ++k) \
;         acc[ai][bj][m][n] = __builtin_amdgcn_mfma_f32_16x16x32_bf16(Bt[n][k], At[m][k], acc[ai][bj][m][n], 0, 0, 0); __builtin_amdgcn_s_setprio(0); } while (0)
; #define PG8_WAIT_V(n) asm volatile("s_waitcnt vmcnt(" #n ")" ::: "memory")
; #define PG8_WAIT_L(n) asm volatile("s_waitcnt lgkmcnt(" #n ")" ::: "memory")
; #define PG8_BAR __builtin_amdgcn_s_barrier()
; #define PG8_SCHED __builtin_amdgcn_sched_barrier(0)
; template <class Epi, class Sched, bool ALIGN_EPI = false, bool SP2 = false>
; __device__ __forceinline__ void gemm_phase(PG8_LAS unsigned char* lds, const Gemm g, const Sched& S, const Epi& E) {
;     ...
;             PG8_WAIT_V(8); PG8_WAIT_L(0); PG8_BAR; PG8_MMA(1, 0, At, B0); PG8_MMA(1, 1, At, B1); PG8_BAR; PG8_SCHED;
;             PG8_LDB(B0, 1, 0); PG8_LDB(B1, 1, 1); PG8_SCHED; PG8_LDA(At, 1, 0); PG8_STAGE(PG8_SA(0, 1), a2 + hstep, voffA);
;             PG8_WAIT_V(8); PG8_WAIT_L(0); PG8_BAR; PG8_MMA(0, 0, At, B0); PG8_MMA(0, 1, At, B1); PG8_BAR; PG8_SCHED;
	s_setprio 1
	v_mfma_f32_16x16x32_bf16 v[28:31], v[132:135], v[202:205], v[28:31]
	v_mfma_f32_16x16x32_bf16 v[24:27], v[140:143], v[202:205], v[24:27]
	v_mfma_f32_16x16x32_bf16 v[12:15], v[132:135], v[210:213], v[12:15]
	v_mfma_f32_16x16x32_bf16 v[8:11], v[140:143], v[210:213], v[8:11]
	v_mfma_f32_16x16x32_bf16 v[64:67], v[136:139], v[182:185], v[64:67]
	v_mfma_f32_16x16x32_bf16 v[60:63], v[144:147], v[182:185], v[60:63]
	v_mfma_f32_16x16x32_bf16 v[48:51], v[136:139], v[190:193], v[48:51]
	v_mfma_f32_16x16x32_bf16 v[44:47], v[144:147], v[190:193], v[44:47]
	v_mfma_f32_16x16x32_bf16 v[28:31], v[136:139], v[206:209], v[28:31]
	v_mfma_f32_16x16x32_bf16 v[24:27], v[144:147], v[206:209], v[24:27]
	v_mfma_f32_16x16x32_bf16 v[12:15], v[136:139], v[214:217], v[12:15]
	v_mfma_f32_16x16x32_bf16 v[8:11], v[144:147], v[214:217], v[8:11]
	s_setprio 0
	s_setprio 1
	v_mfma_f32_16x16x32_bf16 v[56:59], v[158:161], v[178:181], v[56:59]
	v_mfma_f32_16x16x32_bf16 v[52:55], v[166:169], v[178:181], v[52:55]
	v_mfma_f32_16x16x32_bf16 v[40:43], v[158:161], v[186:189], v[40:43]
	v_mfma_f32_16x16x32_bf16 v[36:39], v[166:169], v[186:189], v[36:39]
	v_mfma_f32_16x16x32_bf16 v[20:23], v[158:161], v[202:205], v[20:23]
	v_mfma_f32_16x16x32_bf16 v[16:19], v[166:169], v[202:205], v[16:19]
	v_mfma_f32_16x16x32_bf16 v[4:7], v[158:161], v[210:213], v[4:7]
	v_mfma_f32_16x16x32_bf16 v[0:3], v[166:169], v[210:213], v[0:3]
	v_mfma_f32_16x16x32_bf16 v[56:59], v[162:165], v[182:185], v[56:59]
	v_mfma_f32_16x16x32_bf16 v[52:55], v[174:177], v[182:185], v[52:55]
	v_mfma_f32_16x16x32_bf16 v[40:43], v[162:165], v[190:193], v[40:43]
	v_mfma_f32_16x16x32_bf16 v[36:39], v[174:177], v[190:193], v[36:39]
	v_mfma_f32_16x16x32_bf16 v[20:23], v[162:165], v[206:209], v[20:23]
	v_mfma_f32_16x16x32_bf16 v[16:19], v[174:177], v[206:209], v[16:19]
	v_mfma_f32_16x16x32_bf16 v[4:7], v[162:165], v[214:217], v[4:7]
	v_mfma_f32_16x16x32_bf16 v[0:3], v[174:177], v[214:217], v[0:3]
	s_setprio 0
	s_barrier
	s_add_i32 s60, 0, 0x18000
	s_add_i32 s61, 0, 0x1c000
	v_add_u32_e32 v144, s60, v170
	v_add_u32_e32 v174, s61, v170
	ds_read_b128 v[132:135], v144
	ds_read_b128 v[136:139], v144 offset:1024
	ds_read_b128 v[140:143], v144 offset:2048
	ds_read_b128 v[144:147], v144 offset:3072
	ds_read_b128 v[158:161], v174
	ds_read_b128 v[162:165], v174 offset:1024
	ds_read_b128 v[166:169], v174 offset:2048
	ds_read_b128 v[174:177], v174 offset:3072
	s_add_u32 s42, s42, 0x40000
	s_addc_u32 s43, s43, 0
	s_mov_b32 m0, s52
	v_lshl_add_u64 v[224:225], s[42:43], 0, v[152:153]
	ds_read_b128 v[178:181], v173 offset:32768
	ds_read_b128 v[182:185], v173 offset:33792
	ds_read_b128 v[186:189], v173 offset:34816
	ds_read_b128 v[190:193], v173 offset:35840
	ds_read_b128 v[202:205], v173 offset:36864
	ds_read_b128 v[206:209], v173 offset:37888
	ds_read_b128 v[210:213], v173 offset:38912
	ds_read_b128 v[214:217], v173 offset:39936
	global_load_lds_dwordx4 v[224:225], off
	v_lshl_add_u64 v[224:225], s[42:43], 0, v[148:149]
	s_mov_b32 m0, s53
	s_nop 0
	global_load_lds_dwordx4 v[224:225], off
	s_waitcnt vmcnt(8)
	s_waitcnt lgkmcnt(0)
	v_mfma_f32_16x16x32_bf16 v[128:131], v[132:135], v[178:181], v[128:131]
	v_mfma_f32_16x16x32_bf16 v[124:127], v[140:143], v[178:181], v[124:127]
	v_mfma_f32_16x16x32_bf16 v[112:115], v[132:135], v[186:189], v[112:115]
	v_mfma_f32_16x16x32_bf16 v[108:111], v[140:143], v[186:189], v[108:111]
	s_barrier
	s_setprio 1
	v_mfma_f32_16x16x32_bf16 v[96:99], v[132:135], v[202:205], v[96:99]
	v_mfma_f32_16x16x32_bf16 v[92:95], v[140:143], v[202:205], v[92:95]
	v_mfma_f32_16x16x32_bf16 v[80:83], v[132:135], v[210:213], v[80:83]
	v_mfma_f32_16x16x32_bf16 v[76:79], v[140:143], v[210:213], v[76:79]
	v_mfma_f32_16x16x32_bf16 v[128:131], v[136:139], v[182:185], v[128:131]
	v_mfma_f32_16x16x32_bf16 v[124:127], v[144:147], v[182:185], v[124:127]
	v_mfma_f32_16x16x32_bf16 v[112:115], v[136:139], v[190:193], v[112:115]
	v_mfma_f32_16x16x32_bf16 v[108:111], v[144:147], v[190:193], v[108:111]
	v_mfma_f32_16x16x32_bf16 v[96:99], v[136:139], v[206:209], v[96:99]
	v_mfma_f32_16x16x32_bf16 v[92:95], v[144:147], v[206:209], v[92:95]
	v_mfma_f32_16x16x32_bf16 v[80:83], v[136:139], v[214:217], v[80:83]
	v_mfma_f32_16x16x32_bf16 v[76:79], v[144:147], v[214:217], v[76:79]
	s_setprio 0
	s_setprio 1
	v_mfma_f32_16x16x32_bf16 v[120:123], v[158:161], v[178:181], v[120:123]
	v_mfma_f32_16x16x32_bf16 v[116:119], v[166:169], v[178:181], v[116:119]
	v_mfma_f32_16x16x32_bf16 v[104:107], v[158:161], v[186:189], v[104:107]
	v_mfma_f32_16x16x32_bf16 v[100:103], v[166:169], v[186:189], v[100:103]
	v_mfma_f32_16x16x32_bf16 v[88:91], v[158:161], v[202:205], v[88:91]
	v_mfma_f32_16x16x32_bf16 v[84:87], v[166:169], v[202:205], v[84:87]
	v_mfma_f32_16x16x32_bf16 v[72:75], v[158:161], v[210:213], v[72:75]
	v_mfma_f32_16x16x32_bf16 v[68:71], v[166:169], v[210:213], v[68:71]
	v_mfma_f32_16x16x32_bf16 v[120:123], v[162:165], v[182:185], v[120:123]
	v_mfma_f32_16x16x32_bf16 v[116:119], v[174:177], v[182:185], v[116:119]
	v_mfma_f32_16x16x32_bf16 v[104:107], v[162:165], v[190:193], v[104:107]
	v_mfma_f32_16x16x32_bf16 v[100:103], v[174:177], v[190:193], v[100:103]
	v_mfma_f32_16x16x32_bf16 v[88:91], v[162:165], v[206:209], v[88:91]
	v_mfma_f32_16x16x32_bf16 v[84:87], v[174:177], v[206:209], v[84:87]
	v_mfma_f32_16x16x32_bf16 v[72:75], v[162:165], v[214:217], v[72:75]
	v_mfma_f32_16x16x32_bf16 v[68:71], v[174:177], v[214:217], v[68:71]
	s_setprio 0
	s_barrier
; #define PG8_STAGE(bufoff, gbase, voff) do { _Pragma("unroll") for (int _i = 0; _i < 2; ++_i) \
;         __builtin_amdgcn_global_load_lds((const unsigned*)((const char*)(gbase) + (voff)[_i]), (PG8_LAS unsigned*)(lds + (bufoff) + ldsw + _i * 8192), 16, 0, 0); } while (0)
; #define PG8_LDA(dst, b, h) do { _Pragma("unroll") for (int m = 0; m < 4; ++m) _Pragma("unroll") for (int k = 0; k < 2; ++k) dst[m][k] = *(const PG8_LAS bf16x8*)(lds + PG8_SA(b, h) + aoff + m * 2048 + k * 1024); } while (0)
; #define PG8_LDB(dst, b, h) do { _Pragma("unroll") for (int n = 0; n < 2; ++n) _Pragma("unroll") for (int k = 0; k < 2; ++k) dst[n][k] = *(const PG8_LAS bf16x8*)(lds + PG8_SB(b, h) + boff + n * 2048 + k * 1024); } while (0)
; #define PG8_MMA(ai, bj, At, Bt) do { __builtin_amdgcn_s_setprio(1); _Pragma("unroll") for (int m = 0; m < 4; ++m) _Pragma("unroll") for (int n = 0; n < 2; ++n) _Pragma("unroll") for (int k = 0; k < 2; ++k) \
;         acc[ai][bj][m][n] = __builtin_amdgcn_mfma_f32_16x16x32_bf16(Bt[n][k], At[m][k], acc[ai][bj][m][n], 0, 0, 0); __builtin_amdgcn_s_setprio(0); } while (0)
; #define PG8_WAIT_V(n) asm volatile("s_waitcnt vmcnt(" #n ")" ::: "memory")
; #define PG8_WAIT_L(n) asm volatile("s_waitcnt lgkmcnt(" #n ")" ::: "memory")
; #define PG8_BAR __builtin_amdgcn_s_barrier()
; #define PG8_SCHED __builtin_amdgcn_sched_barrier(0)
; template <class Epi, class Sched, bool ALIGN_EPI = false, bool SP2 = false>
; __device__ __forceinline__ void gemm_phase(PG8_LAS unsigned char* lds, const Gemm g, const Sched& S, const Epi& E) {
;     ...
;             PG8_LDB(B0, 0, 0); PG8_LDB(B1, 0, 1); PG8_SCHED; PG8_LDA(At, 0, 0); PG8_STAGE(PG8_SA(1, 1), a1 + hstep, voffA);
;             PG8_WAIT_V(8); PG8_WAIT_L(0); PG8_BAR; PG8_MMA(0, 0, At, B0); PG8_MMA(0, 1, At, B1); PG8_BAR; PG8_SCHED;
;     ...
;             PG8_LDA(At, 1, 1); PG8_STAGE(PG8_SB(1, 0), b3, voffB); PG8_STAGE(PG8_SB(1, 1), b3 + hstep, voffB); PG8_STAGE(PG8_SA(1, 0), a3, voffA);
;             PG8_WAIT_V(8); PG8_WAIT_L(0); PG8_BAR; PG8_MMA(1, 0, At, B0); PG8_MMA(1, 1, At, B1); PG8_BAR; PG8_SCHED;
	s_add_i32 s42, s60, s49
	v_lshl_add_u64 v[194:195], v[194:195], 0, s[36:37]
	s_mov_b32 m0, s42
	ds_read_b128 v[178:181], v173 offset:49152
	ds_read_b128 v[182:185], v173 offset:50176
	ds_read_b128 v[186:189], v173 offset:51200
	ds_read_b128 v[190:193], v173 offset:52224
	ds_read_b128 v[202:205], v173 offset:53248
	ds_read_b128 v[206:209], v173 offset:54272
	ds_read_b128 v[210:213], v173 offset:55296
	ds_read_b128 v[214:217], v173 offset:56320
	global_load_lds_dwordx4 v[194:195], off
	s_add_i32 m0, s42, 0x2000
	s_add_u32 s4, s4, 0x40080
	v_lshl_add_u64 v[194:195], v[218:219], 0, s[36:37]
	s_addc_u32 s5, s5, 0
	s_add_i32 s42, s61, s49
	global_load_lds_dwordx4 v[194:195], off
	v_lshl_add_u64 v[194:195], s[4:5], 0, v[150:151]
	s_mov_b32 m0, s42
	s_nop 0
	global_load_lds_dwordx4 v[194:195], off
	v_lshl_add_u64 v[194:195], s[4:5], 0, v[32:33]
	s_add_i32 m0, s42, 0x2000
	s_nop 0
	global_load_lds_dwordx4 v[194:195], off
	v_lshl_add_u64 v[194:195], v[220:221], 0, s[36:37]
	s_mov_b32 m0, s54
	s_nop 0
	global_load_lds_dwordx4 v[194:195], off
	v_lshl_add_u64 v[194:195], v[222:223], 0, s[36:37]
	s_mov_b32 m0, s55
	s_nop 0
	global_load_lds_dwordx4 v[194:195], off
	s_waitcnt vmcnt(8)
	s_waitcnt lgkmcnt(0)
	v_mfma_f32_16x16x32_bf16 v[64:67], v[132:135], v[178:181], v[64:67]
	v_mfma_f32_16x16x32_bf16 v[60:63], v[140:143], v[178:181], v[60:63]
	v_mfma_f32_16x16x32_bf16 v[48:51], v[132:135], v[186:189], v[48:51]
	v_mfma_f32_16x16x32_bf16 v[44:47], v[140:143], v[186:189], v[44:47]
	s_barrier
	s_setprio 1
	v_mfma_f32_16x16x32_bf16 v[28:31], v[132:135], v[202:205], v[28:31]
	v_mfma_f32_16x16x32_bf16 v[24:27], v[140:143], v[202:205], v[24:27]
	v_mfma_f32_16x16x32_bf16 v[12:15], v[132:135], v[210:213], v[12:15]
	v_mfma_f32_16x16x32_bf16 v[8:11], v[140:143], v[210:213], v[8:11]
	v_mfma_f32_16x16x32_bf16 v[64:67], v[136:139], v[182:185], v[64:67]
	v_mfma_f32_16x16x32_bf16 v[60:63], v[144:147], v[182:185], v[60:63]
	v_mfma_f32_16x16x32_bf16 v[48:51], v[136:139], v[190:193], v[48:51]
	v_mfma_f32_16x16x32_bf16 v[44:47], v[144:147], v[190:193], v[44:47]
	v_mfma_f32_16x16x32_bf16 v[28:31], v[136:139], v[206:209], v[28:31]
	v_mfma_f32_16x16x32_bf16 v[24:27], v[144:147], v[206:209], v[24:27]
	v_mfma_f32_16x16x32_bf16 v[12:15], v[136:139], v[214:217], v[12:15]
	v_mfma_f32_16x16x32_bf16 v[8:11], v[144:147], v[214:217], v[8:11]
	s_setprio 0
	s_setprio 1
	v_mfma_f32_16x16x32_bf16 v[56:59], v[158:161], v[178:181], v[56:59]
	v_mfma_f32_16x16x32_bf16 v[52:55], v[166:169], v[178:181], v[52:55]
	v_mfma_f32_16x16x32_bf16 v[40:43], v[158:161], v[186:189], v[40:43]
	v_mfma_f32_16x16x32_bf16 v[36:39], v[166:169], v[186:189], v[36:39]
	v_mfma_f32_16x16x32_bf16 v[20:23], v[158:161], v[202:205], v[20:23]
	v_mfma_f32_16x16x32_bf16 v[16:19], v[166:169], v[202:205], v[16:19]
	v_mfma_f32_16x16x32_bf16 v[4:7], v[158:161], v[210:213], v[4:7]
	v_mfma_f32_16x16x32_bf16 v[0:3], v[166:169], v[210:213], v[0:3]
	v_mfma_f32_16x16x32_bf16 v[56:59], v[162:165], v[182:185], v[56:59]
	v_mfma_f32_16x16x32_bf16 v[52:55], v[174:177], v[182:185], v[52:55]
	v_mfma_f32_16x16x32_bf16 v[40:43], v[162:165], v[190:193], v[40:43]
	v_mfma_f32_16x16x32_bf16 v[36:39], v[174:177], v[190:193], v[36:39]
	v_mfma_f32_16x16x32_bf16 v[20:23], v[162:165], v[206:209], v[20:23]
	v_mfma_f32_16x16x32_bf16 v[16:19], v[174:177], v[206:209], v[16:19]
	v_mfma_f32_16x16x32_bf16 v[4:7], v[162:165], v[214:217], v[4:7]
	v_mfma_f32_16x16x32_bf16 v[0:3], v[174:177], v[214:217], v[0:3]
	s_setprio 0
	s_barrier
	s_add_i32 s59, s59, 2
	s_add_u32 s0, s0, 0x100
	s_addc_u32 s1, s1, 0
	s_add_u32 s47, s47, 0x100
	s_addc_u32 s58, s58, 0
	s_cmp_gt_u32 s59, 13
	s_cbranch_scc1 .Lkexit_pg
	s_cmp_eq_u32 s59, 12
	s_cbranch_scc0 .LBB0_342
	s_cmp_lg_u64 s[38:39], 0
	s_cbranch_scc1 .LBB0_342
.Ltail_pg:
	s_add_u32 s4, s0, 0xfffc0080
	s_addc_u32 s5, s1, -1
	s_add_i32 s60, 0, 0x10000
	s_cmp_eq_u32 s59, 12
	s_cselect_b32 s43, s21, s5
	s_cselect_b32 s42, s45, s4
	s_cselect_b32 s5, s19, s58
	s_cselect_b32 s4, s46, s47
	s_add_i32 s62, 0, 0x14000
	v_add_u32_e32 v144, s60, v170
	v_add_u32_e32 v174, s62, v170
	ds_read_b128 v[132:135], v144
	ds_read_b128 v[136:139], v144 offset:1024
	ds_read_b128 v[140:143], v144 offset:2048
	ds_read_b128 v[144:147], v144 offset:3072
	ds_read_b128 v[158:161], v174
	ds_read_b128 v[162:165], v174 offset:1024
	ds_read_b128 v[166:169], v174 offset:2048
	ds_read_b128 v[174:177], v174 offset:3072
	v_lshl_add_u64 v[194:195], s[0:1], 0, v[154:155]
	s_add_i32 m0, s50, 0xc000
	ds_read_b128 v[178:181], v173
	ds_read_b128 v[182:185], v173 offset:1024
	ds_read_b128 v[186:189], v173 offset:2048
	ds_read_b128 v[190:193], v173 offset:3072
	ds_read_b128 v[202:205], v173 offset:4096
	ds_read_b128 v[206:209], v173 offset:5120
	ds_read_b128 v[210:213], v173 offset:6144
	ds_read_b128 v[214:217], v173 offset:7168
	global_load_lds_dwordx4 v[194:195], off
	v_lshl_add_u64 v[194:195], s[0:1], 0, v[156:157]
	s_add_i32 m0, s50, 0xe000
	s_nop 0
	global_load_lds_dwordx4 v[194:195], off
	s_waitcnt vmcnt(8)
	s_waitcnt lgkmcnt(0)
	v_mfma_f32_16x16x32_bf16 v[128:131], v[132:135], v[178:181], v[128:131]
	v_mfma_f32_16x16x32_bf16 v[124:127], v[140:143], v[178:181], v[124:127]
	v_mfma_f32_16x16x32_bf16 v[112:115], v[132:135], v[186:189], v[112:115]
	v_mfma_f32_16x16x32_bf16 v[108:111], v[140:143], v[186:189], v[108:111]
	s_barrier
; #define PG8_STAGE(bufoff, gbase, voff) do { _Pragma("unroll") for (int _i = 0; _i < 2; ++_i) \
;         __builtin_amdgcn_global_load_lds((const unsigned*)((const char*)(gbase) + (voff)[_i]), (PG8_LAS unsigned*)(lds + (bufoff) + ldsw + _i * 8192), 16, 0, 0); } while (0)
; #define PG8_LDA(dst, b, h) do { _Pragma("unroll") for (int m = 0; m < 4; ++m) _Pragma("unroll") for (int k = 0; k < 2; ++k) dst[m][k] = *(const PG8_LAS bf16x8*)(lds + PG8_SA(b, h) + aoff + m * 2048 + k * 1024); } while (0)
; #define PG8_MMA(ai, bj, At, Bt) do { __builtin_amdgcn_s_setprio(1); _Pragma("unroll") for (int m = 0; m < 4; ++m) _Pragma("unroll") for (int n = 0; n < 2; ++n) _Pragma("unroll") for (int k = 0; k < 2; ++k) \
;         acc[ai][bj][m][n] = __builtin_amdgcn_mfma_f32_16x16x32_bf16(Bt[n][k], At[m][k], acc[ai][bj][m][n], 0, 0, 0); __builtin_amdgcn_s_setprio(0); } while (0)
; #define PG8_WAIT_V(n) asm volatile("s_waitcnt vmcnt(" #n ")" ::: "memory")
; #define PG8_WAIT_L(n) asm volatile("s_waitcnt lgkmcnt(" #n ")" ::: "memory")
; #define PG8_BAR __builtin_amdgcn_s_barrier()
; #define PG8_SCHED __builtin_amdgcn_sched_barrier(0)
; template <class Epi, class Sched, bool ALIGN_EPI = false, bool SP2 = false>
; __device__ __forceinline__ void gemm_phase(PG8_LAS unsigned char* lds, const Gemm g, const Sched& S, const Epi& E) {
;     ...
;             PG8_WAIT_V(8); PG8_WAIT_L(0); PG8_BAR; PG8_MMA(0, 0, At, B0); PG8_MMA(0, 1, At, B1); PG8_BAR; PG8_SCHED;
;             PG8_LDA(At, 0, 1); PG8_STAGE(PG8_SB(0, 0), b2, voffB); PG8_STAGE(PG8_SB(0, 1), b2 + hstep, voffB); PG8_STAGE(PG8_SA(0, 0), a2, voffA);
;             PG8_WAIT_V(8); PG8_WAIT_L(0); PG8_BAR; PG8_MMA(1, 0, At, B0); PG8_MMA(1, 1, At, B1); PG8_BAR; PG8_SCHED;
	s_setprio 1
	v_mfma_f32_16x16x32_bf16 v[96:99], v[132:135], v[202:205], v[96:99]
	v_mfma_f32_16x16x32_bf16 v[92:95], v[140:143], v[202:205], v[92:95]
	v_mfma_f32_16x16x32_bf16 v[80:83], v[132:135], v[210:213], v[80:83]
	v_mfma_f32_16x16x32_bf16 v[76:79], v[140:143], v[210:213], v[76:79]
	v_mfma_f32_16x16x32_bf16 v[128:131], v[136:139], v[182:185], v[128:131]
	v_mfma_f32_16x16x32_bf16 v[124:127], v[144:147], v[182:185], v[124:127]
	v_mfma_f32_16x16x32_bf16 v[112:115], v[136:139], v[190:193], v[112:115]
	v_mfma_f32_16x16x32_bf16 v[108:111], v[144:147], v[190:193], v[108:111]
	v_mfma_f32_16x16x32_bf16 v[96:99], v[136:139], v[206:209], v[96:99]
	v_mfma_f32_16x16x32_bf16 v[92:95], v[144:147], v[206:209], v[92:95]
	v_mfma_f32_16x16x32_bf16 v[80:83], v[136:139], v[214:217], v[80:83]
	v_mfma_f32_16x16x32_bf16 v[76:79], v[144:147], v[214:217], v[76:79]
	s_setprio 0
	s_setprio 1
	v_mfma_f32_16x16x32_bf16 v[120:123], v[158:161], v[178:181], v[120:123]
	v_mfma_f32_16x16x32_bf16 v[116:119], v[166:169], v[178:181], v[116:119]
	v_mfma_f32_16x16x32_bf16 v[104:107], v[158:161], v[186:189], v[104:107]
	v_mfma_f32_16x16x32_bf16 v[100:103], v[166:169], v[186:189], v[100:103]
	v_mfma_f32_16x16x32_bf16 v[88:91], v[158:161], v[202:205], v[88:91]
	v_mfma_f32_16x16x32_bf16 v[84:87], v[166:169], v[202:205], v[84:87]
	v_mfma_f32_16x16x32_bf16 v[72:75], v[158:161], v[210:213], v[72:75]
	v_mfma_f32_16x16x32_bf16 v[68:71], v[166:169], v[210:213], v[68:71]
	v_mfma_f32_16x16x32_bf16 v[120:123], v[162:165], v[182:185], v[120:123]
	v_mfma_f32_16x16x32_bf16 v[116:119], v[174:177], v[182:185], v[116:119]
	v_mfma_f32_16x16x32_bf16 v[104:107], v[162:165], v[190:193], v[104:107]
	v_mfma_f32_16x16x32_bf16 v[100:103], v[174:177], v[190:193], v[100:103]
	v_mfma_f32_16x16x32_bf16 v[88:91], v[162:165], v[206:209], v[88:91]
	v_mfma_f32_16x16x32_bf16 v[84:87], v[174:177], v[206:209], v[84:87]
	v_mfma_f32_16x16x32_bf16 v[72:75], v[162:165], v[214:217], v[72:75]
	v_mfma_f32_16x16x32_bf16 v[68:71], v[174:177], v[214:217], v[68:71]
	s_setprio 0
	s_barrier
	s_add_i32 s60, s60, s49
	v_lshl_add_u64 v[194:195], s[4:5], 0, v[150:151]
	s_mov_b32 m0, s60
	ds_read_b128 v[178:181], v173 offset:16384
	ds_read_b128 v[182:185], v173 offset:17408
	ds_read_b128 v[186:189], v173 offset:18432
	ds_read_b128 v[190:193], v173 offset:19456
	ds_read_b128 v[202:205], v173 offset:20480
	ds_read_b128 v[206:209], v173 offset:21504
	ds_read_b128 v[210:213], v173 offset:22528
	ds_read_b128 v[214:217], v173 offset:23552
	s_add_i32 m0, s60, 0x2000
	s_add_u32 s60, s4, 0x40000
	v_lshl_add_u64 v[218:219], s[4:5], 0, v[32:33]
	s_addc_u32 s61, s5, 0
	s_add_i32 s62, s62, s49
	v_lshl_add_u64 v[220:221], s[60:61], 0, v[150:151]
	s_mov_b32 m0, s62
	v_lshl_add_u64 v[222:223], s[42:43], 0, v[148:149]
	v_lshl_add_u64 v[220:221], s[60:61], 0, v[32:33]
	s_add_i32 m0, s62, 0x2000
	s_nop 0
	v_lshl_add_u64 v[220:221], s[42:43], 0, v[152:153]
	s_mov_b32 m0, s50
	s_nop 0
	s_mov_b32 m0, s51
	s_nop 0
	s_waitcnt vmcnt(2)
	s_waitcnt lgkmcnt(0)
	v_mfma_f32_16x16x32_bf16 v[64:67], v[132:135], v[178:181], v[64:67]
	v_mfma_f32_16x16x32_bf16 v[60:63], v[140:143], v[178:181], v[60:63]
	v_mfma_f32_16x16x32_bf16 v[48:51], v[132:135], v[186:189], v[48:51]
	v_mfma_f32_16x16x32_bf16 v[44:47], v[140:143], v[186:189], v[44:47]
	s_barrier
	s_setprio 1
	v_mfma_f32_16x16x32_bf16 v[28:31], v[132:135], v[202:205], v[28:31]
	v_mfma_f32_16x16x32_bf16 v[24:27], v[140:143], v[202:205], v[24:27]
	v_mfma_f32_16x16x32_bf16 v[12:15], v[132:135], v[210:213], v[12:15]
	v_mfma_f32_16x16x32_bf16 v[8:11], v[140:143], v[210:213], v[8:11]
	v_mfma_f32_16x16x32_bf16 v[64:67], v[136:139], v[182:185], v[64:67]
	v_mfma_f32_16x16x32_bf16 v[60:63], v[144:147], v[182:185], v[60:63]
	v_mfma_f32_16x16x32_bf16 v[48:51], v[136:139], v[190:193], v[48:51]
	v_mfma_f32_16x16x32_bf16 v[44:47], v[144:147], v[190:193], v[44:47]
	v_mfma_f32_16x16x32_bf16 v[28:31], v[136:139], v[206:209], v[28:31]
	v_mfma_f32_16x16x32_bf16 v[24:27], v[144:147], v[206:209], v[24:27]
	v_mfma_f32_16x16x32_bf16 v[12:15], v[136:139], v[214:217], v[12:15]
	v_mfma_f32_16x16x32_bf16 v[8:11], v[144:147], v[214:217], v[8:11]
	s_setprio 0
	s_setprio 1
	v_mfma_f32_16x16x32_bf16 v[56:59], v[158:161], v[178:181], v[56:59]
	v_mfma_f32_16x16x32_bf16 v[52:55], v[166:169], v[178:181], v[52:55]
	v_mfma_f32_16x16x32_bf16 v[40:43], v[158:161], v[186:189], v[40:43]
	v_mfma_f32_16x16x32_bf16 v[36:39], v[166:169], v[186:189], v[36:39]
	v_mfma_f32_16x16x32_bf16 v[20:23], v[158:161], v[202:205], v[20:23]
	v_mfma_f32_16x16x32_bf16 v[16:19], v[166:169], v[202:205], v[16:19]
	v_mfma_f32_16x16x32_bf16 v[4:7], v[158:161], v[210:213], v[4:7]
	v_mfma_f32_16x16x32_bf16 v[0:3], v[166:169], v[210:213], v[0:3]
	v_mfma_f32_16x16x32_bf16 v[56:59], v[162:165], v[182:185], v[56:59]
	v_mfma_f32_16x16x32_bf16 v[52:55], v[174:177], v[182:185], v[52:55]
	v_mfma_f32_16x16x32_bf16 v[40:43], v[162:165], v[190:193], v[40:43]
	v_mfma_f32_16x16x32_bf16 v[36:39], v[174:177], v[190:193], v[36:39]
	v_mfma_f32_16x16x32_bf16 v[20:23], v[162:165], v[206:209], v[20:23]
	v_mfma_f32_16x16x32_bf16 v[16:19], v[174:177], v[206:209], v[16:19]
	v_mfma_f32_16x16x32_bf16 v[4:7], v[162:165], v[214:217], v[4:7]
	v_mfma_f32_16x16x32_bf16 v[0:3], v[174:177], v[214:217], v[0:3]
	s_setprio 0
	s_barrier
; #define PG8_STAGE(bufoff, gbase, voff) do { _Pragma("unroll") for (int _i = 0; _i < 2; ++_i) \
;         __builtin_amdgcn_global_load_lds((const unsigned*)((const char*)(gbase) + (voff)[_i]), (PG8_LAS unsigned*)(lds + (bufoff) + ldsw + _i * 8192), 16, 0, 0); } while (0)
; #define PG8_LDA(dst, b, h) do { _Pragma("unroll") for (int m = 0; m < 4; ++m) _Pragma("unroll") for (int k = 0; k < 2; ++k) dst[m][k] = *(const PG8_LAS bf16x8*)(lds + PG8_SA(b, h) + aoff + m * 2048 + k * 1024); } while (0)
; #define PG8_LDB(dst, b, h) do { _Pragma("unroll") for (int n = 0; n < 2; ++n) _Pragma("unroll") for (int k = 0; k < 2; ++k) dst[n][k] = *(const PG8_LAS bf16x8*)(lds + PG8_SB(b, h) + boff + n * 2048 + k * 1024); } while (0)
; #define PG8_MMA(ai, bj, At, Bt) do { __builtin_amdgcn_s_setprio(1); _Pragma("unroll") for (int m = 0; m < 4; ++m) _Pragma("unroll") for (int n = 0; n < 2; ++n) _Pragma("unroll") for (int k = 0; k < 2; ++k) \
;         acc[ai][bj][m][n] = __builtin_amdgcn_mfma_f32_16x16x32_bf16(Bt[n][k], At[m][k], acc[ai][bj][m][n], 0, 0, 0); __builtin_amdgcn_s_setprio(0); } while (0)
; #define PG8_WAIT_V(n) asm volatile("s_waitcnt vmcnt(" #n ")" ::: "memory")
; #define PG8_WAIT_L(n) asm volatile("s_waitcnt lgkmcnt(" #n ")" ::: "memory")
; #define PG8_BAR __builtin_amdgcn_s_barrier()
; #define PG8_SCHED __builtin_amdgcn_sched_barrier(0)
; template <class Epi, class Sched, bool ALIGN_EPI = false, bool SP2 = false>
; __device__ __forceinline__ void gemm_phase(PG8_LAS unsigned char* lds, const Gemm g, const Sched& S, const Epi& E) {
;     ...
;             PG8_LDB(B0, 1, 0); PG8_LDB(B1, 1, 1); PG8_SCHED; PG8_LDA(At, 1, 0); PG8_STAGE(PG8_SA(0, 1), a2 + hstep, voffA);
;             PG8_WAIT_V(8); PG8_WAIT_L(0); PG8_BAR; PG8_MMA(0, 0, At, B0); PG8_MMA(0, 1, At, B1); PG8_BAR; PG8_SCHED;
;             PG8_LDA(At, 1, 1); PG8_STAGE(PG8_SB(1, 0), b3, voffB); PG8_STAGE(PG8_SB(1, 1), b3 + hstep, voffB); PG8_STAGE(PG8_SA(1, 0), a3, voffA);
;             PG8_WAIT_V(8); PG8_WAIT_L(0); PG8_BAR; PG8_MMA(1, 0, At, B0); PG8_MMA(1, 1, At, B1); PG8_BAR; PG8_SCHED;
;     ...
;         if constexpr (ALIGN_EPI) { if (wr == 0) PG8_BAR; }
	s_add_i32 s60, 0, 0x18000
	s_add_i32 s61, 0, 0x1c000
	v_add_u32_e32 v144, s60, v170
	v_add_u32_e32 v174, s61, v170
	ds_read_b128 v[132:135], v144
	ds_read_b128 v[136:139], v144 offset:1024
	ds_read_b128 v[140:143], v144 offset:2048
	ds_read_b128 v[144:147], v144 offset:3072
	ds_read_b128 v[158:161], v174
	ds_read_b128 v[162:165], v174 offset:1024
	ds_read_b128 v[166:169], v174 offset:2048
	ds_read_b128 v[174:177], v174 offset:3072
	s_add_u32 s42, s42, 0x40000
	s_addc_u32 s43, s43, 0
	s_mov_b32 m0, s52
	v_lshl_add_u64 v[224:225], s[42:43], 0, v[152:153]
	ds_read_b128 v[178:181], v173 offset:32768
	ds_read_b128 v[182:185], v173 offset:33792
	ds_read_b128 v[186:189], v173 offset:34816
	ds_read_b128 v[190:193], v173 offset:35840
	ds_read_b128 v[202:205], v173 offset:36864
	ds_read_b128 v[206:209], v173 offset:37888
	ds_read_b128 v[210:213], v173 offset:38912
	ds_read_b128 v[214:217], v173 offset:39936
	v_lshl_add_u64 v[224:225], s[42:43], 0, v[148:149]
	s_mov_b32 m0, s53
	s_nop 0
	s_waitcnt vmcnt(0)
	s_waitcnt lgkmcnt(0)
	v_mfma_f32_16x16x32_bf16 v[128:131], v[132:135], v[178:181], v[128:131]
	v_mfma_f32_16x16x32_bf16 v[124:127], v[140:143], v[178:181], v[124:127]
	v_mfma_f32_16x16x32_bf16 v[112:115], v[132:135], v[186:189], v[112:115]
	v_mfma_f32_16x16x32_bf16 v[108:111], v[140:143], v[186:189], v[108:111]
	s_barrier
	s_setprio 1
	v_mfma_f32_16x16x32_bf16 v[96:99], v[132:135], v[202:205], v[96:99]
	v_mfma_f32_16x16x32_bf16 v[92:95], v[140:143], v[202:205], v[92:95]
	v_mfma_f32_16x16x32_bf16 v[80:83], v[132:135], v[210:213], v[80:83]
	v_mfma_f32_16x16x32_bf16 v[76:79], v[140:143], v[210:213], v[76:79]
	v_mfma_f32_16x16x32_bf16 v[128:131], v[136:139], v[182:185], v[128:131]
	v_mfma_f32_16x16x32_bf16 v[124:127], v[144:147], v[182:185], v[124:127]
	v_mfma_f32_16x16x32_bf16 v[112:115], v[136:139], v[190:193], v[112:115]
	v_mfma_f32_16x16x32_bf16 v[108:111], v[144:147], v[190:193], v[108:111]
	v_mfma_f32_16x16x32_bf16 v[96:99], v[136:139], v[206:209], v[96:99]
	v_mfma_f32_16x16x32_bf16 v[92:95], v[144:147], v[206:209], v[92:95]
	v_mfma_f32_16x16x32_bf16 v[80:83], v[136:139], v[214:217], v[80:83]
	v_mfma_f32_16x16x32_bf16 v[76:79], v[144:147], v[214:217], v[76:79]
	s_setprio 0
	s_setprio 1
	v_mfma_f32_16x16x32_bf16 v[120:123], v[158:161], v[178:181], v[120:123]
	v_mfma_f32_16x16x32_bf16 v[116:119], v[166:169], v[178:181], v[116:119]
	v_mfma_f32_16x16x32_bf16 v[104:107], v[158:161], v[186:189], v[104:107]
	v_mfma_f32_16x16x32_bf16 v[100:103], v[166:169], v[186:189], v[100:103]
	v_mfma_f32_16x16x32_bf16 v[88:91], v[158:161], v[202:205], v[88:91]
	v_mfma_f32_16x16x32_bf16 v[84:87], v[166:169], v[202:205], v[84:87]
	v_mfma_f32_16x16x32_bf16 v[72:75], v[158:161], v[210:213], v[72:75]
	v_mfma_f32_16x16x32_bf16 v[68:71], v[166:169], v[210:213], v[68:71]
	v_mfma_f32_16x16x32_bf16 v[120:123], v[162:165], v[182:185], v[120:123]
	v_mfma_f32_16x16x32_bf16 v[116:119], v[174:177], v[182:185], v[116:119]
	v_mfma_f32_16x16x32_bf16 v[104:107], v[162:165], v[190:193], v[104:107]
	v_mfma_f32_16x16x32_bf16 v[100:103], v[174:177], v[190:193], v[100:103]
	v_mfma_f32_16x16x32_bf16 v[88:91], v[162:165], v[206:209], v[88:91]
	v_mfma_f32_16x16x32_bf16 v[84:87], v[174:177], v[206:209], v[84:87]
	v_mfma_f32_16x16x32_bf16 v[72:75], v[162:165], v[214:217], v[72:75]
	v_mfma_f32_16x16x32_bf16 v[68:71], v[174:177], v[214:217], v[68:71]
	s_setprio 0
	s_barrier
	s_add_i32 s42, s60, s49
	v_lshl_add_u64 v[194:195], v[194:195], 0, s[36:37]
	s_mov_b32 m0, s42
	ds_read_b128 v[178:181], v173 offset:49152
	ds_read_b128 v[182:185], v173 offset:50176
	ds_read_b128 v[186:189], v173 offset:51200
	ds_read_b128 v[190:193], v173 offset:52224
	ds_read_b128 v[202:205], v173 offset:53248
	ds_read_b128 v[206:209], v173 offset:54272
	ds_read_b128 v[210:213], v173 offset:55296
	ds_read_b128 v[214:217], v173 offset:56320
	s_add_i32 m0, s42, 0x2000
	s_add_u32 s4, s4, 0x40080
	v_lshl_add_u64 v[194:195], v[218:219], 0, s[36:37]
	s_addc_u32 s5, s5, 0
	s_add_i32 s42, s61, s49
	v_lshl_add_u64 v[194:195], s[4:5], 0, v[150:151]
	s_mov_b32 m0, s42
	s_nop 0
	v_lshl_add_u64 v[194:195], s[4:5], 0, v[32:33]
	s_add_i32 m0, s42, 0x2000
	s_nop 0
	v_lshl_add_u64 v[194:195], v[220:221], 0, s[36:37]
	s_mov_b32 m0, s54
	s_nop 0
	v_lshl_add_u64 v[194:195], v[222:223], 0, s[36:37]
	s_mov_b32 m0, s55
	s_nop 0
	s_waitcnt vmcnt(0)
	s_waitcnt lgkmcnt(0)
	v_mfma_f32_16x16x32_bf16 v[64:67], v[132:135], v[178:181], v[64:67]
	v_mfma_f32_16x16x32_bf16 v[60:63], v[140:143], v[178:181], v[60:63]
	v_mfma_f32_16x16x32_bf16 v[48:51], v[132:135], v[186:189], v[48:51]
	v_mfma_f32_16x16x32_bf16 v[44:47], v[140:143], v[186:189], v[44:47]
	s_barrier
	s_setprio 1
	v_mfma_f32_16x16x32_bf16 v[28:31], v[132:135], v[202:205], v[28:31]
	v_mfma_f32_16x16x32_bf16 v[24:27], v[140:143], v[202:205], v[24:27]
	v_mfma_f32_16x16x32_bf16 v[12:15], v[132:135], v[210:213], v[12:15]
	v_mfma_f32_16x16x32_bf16 v[8:11], v[140:143], v[210:213], v[8:11]
	v_mfma_f32_16x16x32_bf16 v[64:67], v[136:139], v[182:185], v[64:67]
	v_mfma_f32_16x16x32_bf16 v[60:63], v[144:147], v[182:185], v[60:63]
	v_mfma_f32_16x16x32_bf16 v[48:51], v[136:139], v[190:193], v[48:51]
	v_mfma_f32_16x16x32_bf16 v[44:47], v[144:147], v[190:193], v[44:47]
	v_mfma_f32_16x16x32_bf16 v[28:31], v[136:139], v[206:209], v[28:31]
	v_mfma_f32_16x16x32_bf16 v[24:27], v[144:147], v[206:209], v[24:27]
	v_mfma_f32_16x16x32_bf16 v[12:15], v[136:139], v[214:217], v[12:15]
	v_mfma_f32_16x16x32_bf16 v[8:11], v[144:147], v[214:217], v[8:11]
	s_setprio 0
	s_setprio 1
	v_mfma_f32_16x16x32_bf16 v[56:59], v[158:161], v[178:181], v[56:59]
	v_mfma_f32_16x16x32_bf16 v[52:55], v[166:169], v[178:181], v[52:55]
	v_mfma_f32_16x16x32_bf16 v[40:43], v[158:161], v[186:189], v[40:43]
	v_mfma_f32_16x16x32_bf16 v[36:39], v[166:169], v[186:189], v[36:39]
	v_mfma_f32_16x16x32_bf16 v[20:23], v[158:161], v[202:205], v[20:23]
	v_mfma_f32_16x16x32_bf16 v[16:19], v[166:169], v[202:205], v[16:19]
	v_mfma_f32_16x16x32_bf16 v[4:7], v[158:161], v[210:213], v[4:7]
	v_mfma_f32_16x16x32_bf16 v[0:3], v[166:169], v[210:213], v[0:3]
	v_mfma_f32_16x16x32_bf16 v[56:59], v[162:165], v[182:185], v[56:59]
	v_mfma_f32_16x16x32_bf16 v[52:55], v[174:177], v[182:185], v[52:55]
	v_mfma_f32_16x16x32_bf16 v[40:43], v[162:165], v[190:193], v[40:43]
	v_mfma_f32_16x16x32_bf16 v[36:39], v[174:177], v[190:193], v[36:39]
	v_mfma_f32_16x16x32_bf16 v[20:23], v[162:165], v[206:209], v[20:23]
	v_mfma_f32_16x16x32_bf16 v[16:19], v[174:177], v[206:209], v[16:19]
	v_mfma_f32_16x16x32_bf16 v[4:7], v[162:165], v[214:217], v[4:7]
	v_mfma_f32_16x16x32_bf16 v[0:3], v[174:177], v[214:217], v[0:3]
	s_setprio 0
	s_barrier
	s_add_i32 s59, s59, 2
	s_add_u32 s0, s0, 0x100
	s_addc_u32 s1, s1, 0
	s_add_u32 s47, s47, 0x100
	s_addc_u32 s58, s58, 0
.Lkexit_pg:
	s_and_b64 vcc, exec, s[16:17]
	s_cbranch_vccz .LBB0_345
	s_barrier

; #define PG8_STAGE(bufoff, gbase, voff) do { _Pragma("unroll") for (int _i = 0; _i < 2; ++_i) \
;         __builtin_amdgcn_global_load_lds((const unsigned*)((const char*)(gbase) + (voff)[_i]), (PG8_LAS unsigned*)(lds + (bufoff) + ldsw + _i * 8192), 16, 0, 0); } while (0)
; #define PG8_LDA(dst, b, h) do { _Pragma("unroll") for (int m = 0; m < 4; ++m) _Pragma("unroll") for (int k = 0; k < 2; ++k) dst[m][k] = *(const PG8_LAS bf16x8*)(lds + PG8_SA(b, h) + aoff + m * 2048 + k * 1024); } while (0)
; #define PG8_LDB(dst, b, h) do { _Pragma("unroll") for (int n = 0; n < 2; ++n) _Pragma("unroll") for (int k = 0; k < 2; ++k) dst[n][k] = *(const PG8_LAS bf16x8*)(lds + PG8_SB(b, h) + boff + n * 2048 + k * 1024); } while (0)
; #define PG8_MMA(ai, bj, At, Bt) do { __builtin_amdgcn_s_setprio(1); _Pragma("unroll") for (int m = 0; m < 4; ++m) _Pragma("unroll") for (int n = 0; n < 2; ++n) _Pragma("unroll") for (int k = 0; k < 2; ++k) \
;         acc[ai][bj][m][n] = __builtin_amdgcn_mfma_f32_16x16x32_bf16(Bt[n][k], At[m][k], acc[ai][bj][m][n], 0, 0, 0); __builtin_amdgcn_s_setprio(0); } while (0)
; #define PG8_WAIT_V(n) asm volatile("s_waitcnt vmcnt(" #n ")" ::: "memory")
; #define PG8_WAIT_L(n) asm volatile("s_waitcnt lgkmcnt(" #n ")" ::: "memory")
; template <class Epi, class Sched, bool ALIGN_EPI = false, bool SP2 = false>
; __device__ __forceinline__ void gemm_phase(PG8_LAS unsigned char* lds, const Gemm g, const Sched& S, const Epi& E) {
;     ...
;             const bool last = (t == nt - 2);
;             const char* a1 = cA + (size_t)(t + 1) * kstep;
;             const char* a2 = last ? nA : cA + (size_t)(t + 2) * kstep; const char* b2 = last ? nB : cB + (size_t)(t + 2) * kstep;
;             const char* a3 = a2 + kstep; const char* b3 = b2 + kstep;
;             if (last && has_next) S.a_ready(nxt);
;             if constexpr (SP2) {
;             PG8_LDB(B0, 0, 0); PG8_LDB(B1, 0, 1); PG8_SCHED; PG8_LDA(At, 0, 0); PG8_STAGE(PG8_SA(1, 1), a1 + hstep, voffA);
;             PG8_WAIT_V(8); PG8_WAIT_L(0); PG8_BAR; PG8_MMA(0, 0, At, B0); PG8_MMA(0, 1, At, B1); PG8_BAR; PG8_SCHED;
;             PG8_LDA(At, 0, 1); PG8_STAGE(PG8_SB(0, 0), b2, voffB); PG8_STAGE(PG8_SB(0, 1), b2 + hstep, voffB); PG8_STAGE(PG8_SA(0, 0), a2, voffA);
;             PG8_WAIT_V(8); PG8_WAIT_L(0); PG8_BAR; PG8_MMA(1, 0, At, B0); PG8_MMA(1, 1, At, B1); PG8_BAR; PG8_SCHED;
.LBB0_623:
	s_add_u32 s22, s0, 0xfffc0080
	s_addc_u32 s23, s1, -1
	s_add_i32 s58, 0, 0x10000
	s_cmp_eq_u32 s57, 12
	s_cselect_b32 s41, s17, s23
	s_cselect_b32 s40, s53, s22
	v_add_u32_e32 v144, s58, v147
	s_cselect_b32 s23, s15, s56
	s_cselect_b32 s22, s54, s55
	s_add_i32 s60, 0, 0x14000
	ds_read_b128 v[140:143], v144
	ds_read_b128 v[150:153], v144 offset:1024
	ds_read_b128 v[154:157], v144 offset:2048
	ds_read_b128 v[158:161], v144 offset:3072
	v_add_u32_e32 v144, s60, v147
	ds_read_b128 v[162:165], v144
	ds_read_b128 v[166:169], v144 offset:1024
	ds_read_b128 v[170:173], v144 offset:2048
	ds_read_b128 v[174:177], v144 offset:3072
	v_lshl_add_u64 v[144:145], s[0:1], 0, v[136:137]
	s_add_i32 m0, s44, 0xc000
	ds_read_b128 v[178:181], v149
	ds_read_b128 v[182:185], v149 offset:1024
	ds_read_b128 v[186:189], v149 offset:2048
	ds_read_b128 v[190:193], v149 offset:3072
	ds_read_b128 v[202:205], v149 offset:4096
	ds_read_b128 v[206:209], v149 offset:5120
	ds_read_b128 v[210:213], v149 offset:6144
	ds_read_b128 v[214:217], v149 offset:7168
	global_load_lds_dwordx4 v[144:145], off
	v_lshl_add_u64 v[144:145], s[0:1], 0, v[138:139]
	s_add_i32 m0, s44, 0xe000
	s_nop 0
	global_load_lds_dwordx4 v[144:145], off
	s_waitcnt vmcnt(8)
	s_waitcnt lgkmcnt(0)
	v_mfma_f32_16x16x32_bf16 v[128:131], v[140:143], v[178:181], v[128:131]
	v_mfma_f32_16x16x32_bf16 v[124:127], v[154:157], v[178:181], v[124:127]
	v_mfma_f32_16x16x32_bf16 v[112:115], v[140:143], v[186:189], v[112:115]
	v_mfma_f32_16x16x32_bf16 v[108:111], v[154:157], v[186:189], v[108:111]
	s_barrier
	s_setprio 1
	v_mfma_f32_16x16x32_bf16 v[96:99], v[140:143], v[202:205], v[96:99]
	v_mfma_f32_16x16x32_bf16 v[92:95], v[154:157], v[202:205], v[92:95]
	v_mfma_f32_16x16x32_bf16 v[80:83], v[140:143], v[210:213], v[80:83]
	v_mfma_f32_16x16x32_bf16 v[76:79], v[154:157], v[210:213], v[76:79]
	v_mfma_f32_16x16x32_bf16 v[128:131], v[150:153], v[182:185], v[128:131]
	v_mfma_f32_16x16x32_bf16 v[124:127], v[158:161], v[182:185], v[124:127]
	v_mfma_f32_16x16x32_bf16 v[112:115], v[150:153], v[190:193], v[112:115]
	v_mfma_f32_16x16x32_bf16 v[108:111], v[158:161], v[190:193], v[108:111]
	v_mfma_f32_16x16x32_bf16 v[96:99], v[150:153], v[206:209], v[96:99]
	v_mfma_f32_16x16x32_bf16 v[92:95], v[158:161], v[206:209], v[92:95]
	v_mfma_f32_16x16x32_bf16 v[80:83], v[150:153], v[214:217], v[80:83]
	v_mfma_f32_16x16x32_bf16 v[76:79], v[158:161], v[214:217], v[76:79]
	s_setprio 0
	s_setprio 1
	v_mfma_f32_16x16x32_bf16 v[120:123], v[162:165], v[178:181], v[120:123]
	v_mfma_f32_16x16x32_bf16 v[116:119], v[170:173], v[178:181], v[116:119]
	v_mfma_f32_16x16x32_bf16 v[104:107], v[162:165], v[186:189], v[104:107]
	v_mfma_f32_16x16x32_bf16 v[100:103], v[170:173], v[186:189], v[100:103]
	v_mfma_f32_16x16x32_bf16 v[88:91], v[162:165], v[202:205], v[88:91]
	v_mfma_f32_16x16x32_bf16 v[84:87], v[170:173], v[202:205], v[84:87]
	v_mfma_f32_16x16x32_bf16 v[72:75], v[162:165], v[210:213], v[72:75]
	v_mfma_f32_16x16x32_bf16 v[68:71], v[170:173], v[210:213], v[68:71]
	v_mfma_f32_16x16x32_bf16 v[120:123], v[166:169], v[182:185], v[120:123]
	v_mfma_f32_16x16x32_bf16 v[116:119], v[174:177], v[182:185], v[116:119]
	v_mfma_f32_16x16x32_bf16 v[104:107], v[166:169], v[190:193], v[104:107]
	v_mfma_f32_16x16x32_bf16 v[100:103], v[174:177], v[190:193], v[100:103]
	v_mfma_f32_16x16x32_bf16 v[88:91], v[166:169], v[206:209], v[88:91]
	v_mfma_f32_16x16x32_bf16 v[84:87], v[174:177], v[206:209], v[84:87]
	v_mfma_f32_16x16x32_bf16 v[72:75], v[166:169], v[214:217], v[72:75]
	v_mfma_f32_16x16x32_bf16 v[68:71], v[174:177], v[214:217], v[68:71]
	s_setprio 0
	s_barrier
	s_add_i32 s58, s58, s43
	v_lshl_add_u64 v[144:145], s[22:23], 0, v[196:197]
	s_mov_b32 m0, s58
	ds_read_b128 v[178:181], v149 offset:16384
	ds_read_b128 v[182:185], v149 offset:17408
	ds_read_b128 v[186:189], v149 offset:18432
	ds_read_b128 v[190:193], v149 offset:19456
	ds_read_b128 v[202:205], v149 offset:20480
	ds_read_b128 v[206:209], v149 offset:21504
	ds_read_b128 v[210:213], v149 offset:22528
	ds_read_b128 v[214:217], v149 offset:23552
	global_load_lds_dwordx4 v[144:145], off
	s_add_i32 m0, s58, 0x2000
	s_add_u32 s58, s22, 0x40000
	v_lshl_add_u64 v[194:195], s[22:23], 0, v[32:33]
	s_addc_u32 s59, s23, 0
	s_add_i32 s60, s60, s43
	global_load_lds_dwordx4 v[194:195], off
	v_lshl_add_u64 v[218:219], s[58:59], 0, v[196:197]
	s_mov_b32 m0, s60
	v_lshl_add_u64 v[220:221], s[40:41], 0, v[132:133]
	global_load_lds_dwordx4 v[218:219], off
	v_lshl_add_u64 v[218:219], s[58:59], 0, v[32:33]
	s_add_i32 m0, s60, 0x2000
	s_nop 0
	global_load_lds_dwordx4 v[218:219], off
	v_lshl_add_u64 v[218:219], s[40:41], 0, v[134:135]
	s_mov_b32 m0, s44
	s_nop 0
	global_load_lds_dwordx4 v[218:219], off
	s_mov_b32 m0, s45
	s_nop 0
	global_load_lds_dwordx4 v[220:221], off
	s_waitcnt vmcnt(8)
	s_waitcnt lgkmcnt(0)
	v_mfma_f32_16x16x32_bf16 v[64:67], v[140:143], v[178:181], v[64:67]
	v_mfma_f32_16x16x32_bf16 v[60:63], v[154:157], v[178:181], v[60:63]
	v_mfma_f32_16x16x32_bf16 v[48:51], v[140:143], v[186:189], v[48:51]
	v_mfma_f32_16x16x32_bf16 v[44:47], v[154:157], v[186:189], v[44:47]
	s_barrier
; #define PG8_STAGE(bufoff, gbase, voff) do { _Pragma("unroll") for (int _i = 0; _i < 2; ++_i) \
;         __builtin_amdgcn_global_load_lds((const unsigned*)((const char*)(gbase) + (voff)[_i]), (PG8_LAS unsigned*)(lds + (bufoff) + ldsw + _i * 8192), 16, 0, 0); } while (0)
; #define PG8_LDA(dst, b, h) do { _Pragma("unroll") for (int m = 0; m < 4; ++m) _Pragma("unroll") for (int k = 0; k < 2; ++k) dst[m][k] = *(const PG8_LAS bf16x8*)(lds + PG8_SA(b, h) + aoff + m * 2048 + k * 1024); } while (0)
; #define PG8_LDB(dst, b, h) do { _Pragma("unroll") for (int n = 0; n < 2; ++n) _Pragma("unroll") for (int k = 0; k < 2; ++k) dst[n][k] = *(const PG8_LAS bf16x8*)(lds + PG8_SB(b, h) + boff + n * 2048 + k * 1024); } while (0)
; #define PG8_MMA(ai, bj, At, Bt) do { __builtin_amdgcn_s_setprio(1); _Pragma("unroll") for (int m = 0; m < 4; ++m) _Pragma("unroll") for (int n = 0; n < 2; ++n) _Pragma("unroll") for (int k = 0; k < 2; ++k) \
;         acc[ai][bj][m][n] = __builtin_amdgcn_mfma_f32_16x16x32_bf16(Bt[n][k], At[m][k], acc[ai][bj][m][n], 0, 0, 0); __builtin_amdgcn_s_setprio(0); } while (0)
; #define PG8_WAIT_V(n) asm volatile("s_waitcnt vmcnt(" #n ")" ::: "memory")
; #define PG8_WAIT_L(n) asm volatile("s_waitcnt lgkmcnt(" #n ")" ::: "memory")
; #define PG8_BAR __builtin_amdgcn_s_barrier()
; #define PG8_SCHED __builtin_amdgcn_sched_barrier(0)
; template <class Epi, class Sched, bool ALIGN_EPI = false, bool SP2 = false>
; __device__ __forceinline__ void gemm_phase(PG8_LAS unsigned char* lds, const Gemm g, const Sched& S, const Epi& E) {
;     ...
;             PG8_WAIT_V(8); PG8_WAIT_L(0); PG8_BAR; PG8_MMA(1, 0, At, B0); PG8_MMA(1, 1, At, B1); PG8_BAR; PG8_SCHED;
;             PG8_LDB(B0, 1, 0); PG8_LDB(B1, 1, 1); PG8_SCHED; PG8_LDA(At, 1, 0); PG8_STAGE(PG8_SA(0, 1), a2 + hstep, voffA);
;             PG8_WAIT_V(8); PG8_WAIT_L(0); PG8_BAR; PG8_MMA(0, 0, At, B0); PG8_MMA(0, 1, At, B1); PG8_BAR; PG8_SCHED;
	s_setprio 1
	v_mfma_f32_16x16x32_bf16 v[28:31], v[140:143], v[202:205], v[28:31]
	v_mfma_f32_16x16x32_bf16 v[24:27], v[154:157], v[202:205], v[24:27]
	v_mfma_f32_16x16x32_bf16 v[12:15], v[140:143], v[210:213], v[12:15]
	v_mfma_f32_16x16x32_bf16 v[8:11], v[154:157], v[210:213], v[8:11]
	v_mfma_f32_16x16x32_bf16 v[64:67], v[150:153], v[182:185], v[64:67]
	v_mfma_f32_16x16x32_bf16 v[60:63], v[158:161], v[182:185], v[60:63]
	v_mfma_f32_16x16x32_bf16 v[48:51], v[150:153], v[190:193], v[48:51]
	v_mfma_f32_16x16x32_bf16 v[44:47], v[158:161], v[190:193], v[44:47]
	v_mfma_f32_16x16x32_bf16 v[28:31], v[150:153], v[206:209], v[28:31]
	v_mfma_f32_16x16x32_bf16 v[24:27], v[158:161], v[206:209], v[24:27]
	v_mfma_f32_16x16x32_bf16 v[12:15], v[150:153], v[214:217], v[12:15]
	v_mfma_f32_16x16x32_bf16 v[8:11], v[158:161], v[214:217], v[8:11]
	s_setprio 0
	s_setprio 1
	v_mfma_f32_16x16x32_bf16 v[56:59], v[162:165], v[178:181], v[56:59]
	v_mfma_f32_16x16x32_bf16 v[52:55], v[170:173], v[178:181], v[52:55]
	v_mfma_f32_16x16x32_bf16 v[40:43], v[162:165], v[186:189], v[40:43]
	v_mfma_f32_16x16x32_bf16 v[36:39], v[170:173], v[186:189], v[36:39]
	v_mfma_f32_16x16x32_bf16 v[20:23], v[162:165], v[202:205], v[20:23]
	v_mfma_f32_16x16x32_bf16 v[16:19], v[170:173], v[202:205], v[16:19]
	v_mfma_f32_16x16x32_bf16 v[4:7], v[162:165], v[210:213], v[4:7]
	v_mfma_f32_16x16x32_bf16 v[0:3], v[170:173], v[210:213], v[0:3]
	v_mfma_f32_16x16x32_bf16 v[56:59], v[166:169], v[182:185], v[56:59]
	v_mfma_f32_16x16x32_bf16 v[52:55], v[174:177], v[182:185], v[52:55]
	v_mfma_f32_16x16x32_bf16 v[40:43], v[166:169], v[190:193], v[40:43]
	v_mfma_f32_16x16x32_bf16 v[36:39], v[174:177], v[190:193], v[36:39]
	v_mfma_f32_16x16x32_bf16 v[20:23], v[166:169], v[206:209], v[20:23]
	v_mfma_f32_16x16x32_bf16 v[16:19], v[174:177], v[206:209], v[16:19]
	v_mfma_f32_16x16x32_bf16 v[4:7], v[166:169], v[214:217], v[4:7]
	v_mfma_f32_16x16x32_bf16 v[0:3], v[174:177], v[214:217], v[0:3]
	s_setprio 0
	s_barrier
	s_add_i32 s58, 0, 0x18000
	v_add_u32_e32 v146, s58, v147
	s_add_i32 s59, 0, 0x1c000
	ds_read_b128 v[140:143], v146
	ds_read_b128 v[150:153], v146 offset:1024
	ds_read_b128 v[154:157], v146 offset:2048
	ds_read_b128 v[158:161], v146 offset:3072
	v_add_u32_e32 v146, s59, v147
	ds_read_b128 v[162:165], v146
	ds_read_b128 v[166:169], v146 offset:1024
	ds_read_b128 v[170:173], v146 offset:2048
	ds_read_b128 v[174:177], v146 offset:3072
	s_add_u32 s40, s40, 0x40000
	s_addc_u32 s41, s41, 0
	s_mov_b32 m0, s46
	v_lshl_add_u64 v[222:223], s[40:41], 0, v[134:135]
	ds_read_b128 v[178:181], v149 offset:32768
	ds_read_b128 v[182:185], v149 offset:33792
	ds_read_b128 v[186:189], v149 offset:34816
	ds_read_b128 v[190:193], v149 offset:35840
	ds_read_b128 v[202:205], v149 offset:36864
	ds_read_b128 v[206:209], v149 offset:37888
	ds_read_b128 v[210:213], v149 offset:38912
	ds_read_b128 v[214:217], v149 offset:39936
	global_load_lds_dwordx4 v[222:223], off
	v_lshl_add_u64 v[222:223], s[40:41], 0, v[132:133]
	s_mov_b32 m0, s47
	s_nop 0
	global_load_lds_dwordx4 v[222:223], off
	s_waitcnt vmcnt(8)
	s_waitcnt lgkmcnt(0)
	v_mfma_f32_16x16x32_bf16 v[128:131], v[140:143], v[178:181], v[128:131]
	v_mfma_f32_16x16x32_bf16 v[124:127], v[154:157], v[178:181], v[124:127]
	v_mfma_f32_16x16x32_bf16 v[112:115], v[140:143], v[186:189], v[112:115]
	v_mfma_f32_16x16x32_bf16 v[108:111], v[154:157], v[186:189], v[108:111]
	s_barrier
	s_setprio 1
	v_mfma_f32_16x16x32_bf16 v[96:99], v[140:143], v[202:205], v[96:99]
	v_mfma_f32_16x16x32_bf16 v[92:95], v[154:157], v[202:205], v[92:95]
	v_mfma_f32_16x16x32_bf16 v[80:83], v[140:143], v[210:213], v[80:83]
	v_mfma_f32_16x16x32_bf16 v[76:79], v[154:157], v[210:213], v[76:79]
	v_mfma_f32_16x16x32_bf16 v[128:131], v[150:153], v[182:185], v[128:131]
	v_mfma_f32_16x16x32_bf16 v[124:127], v[158:161], v[182:185], v[124:127]
	v_mfma_f32_16x16x32_bf16 v[112:115], v[150:153], v[190:193], v[112:115]
	v_mfma_f32_16x16x32_bf16 v[108:111], v[158:161], v[190:193], v[108:111]
	v_mfma_f32_16x16x32_bf16 v[96:99], v[150:153], v[206:209], v[96:99]
	v_mfma_f32_16x16x32_bf16 v[92:95], v[158:161], v[206:209], v[92:95]
	v_mfma_f32_16x16x32_bf16 v[80:83], v[150:153], v[214:217], v[80:83]
	v_mfma_f32_16x16x32_bf16 v[76:79], v[158:161], v[214:217], v[76:79]
	s_setprio 0
	s_setprio 1
	v_mfma_f32_16x16x32_bf16 v[120:123], v[162:165], v[178:181], v[120:123]
	v_mfma_f32_16x16x32_bf16 v[116:119], v[170:173], v[178:181], v[116:119]
	v_mfma_f32_16x16x32_bf16 v[104:107], v[162:165], v[186:189], v[104:107]
	v_mfma_f32_16x16x32_bf16 v[100:103], v[170:173], v[186:189], v[100:103]
	v_mfma_f32_16x16x32_bf16 v[88:91], v[162:165], v[202:205], v[88:91]
	v_mfma_f32_16x16x32_bf16 v[84:87], v[170:173], v[202:205], v[84:87]
	v_mfma_f32_16x16x32_bf16 v[72:75], v[162:165], v[210:213], v[72:75]
	v_mfma_f32_16x16x32_bf16 v[68:71], v[170:173], v[210:213], v[68:71]
	v_mfma_f32_16x16x32_bf16 v[120:123], v[166:169], v[182:185], v[120:123]
	v_mfma_f32_16x16x32_bf16 v[116:119], v[174:177], v[182:185], v[116:119]
	v_mfma_f32_16x16x32_bf16 v[104:107], v[166:169], v[190:193], v[104:107]
	v_mfma_f32_16x16x32_bf16 v[100:103], v[174:177], v[190:193], v[100:103]
	v_mfma_f32_16x16x32_bf16 v[88:91], v[166:169], v[206:209], v[88:91]
	v_mfma_f32_16x16x32_bf16 v[84:87], v[174:177], v[206:209], v[84:87]
	v_mfma_f32_16x16x32_bf16 v[72:75], v[166:169], v[214:217], v[72:75]
	v_mfma_f32_16x16x32_bf16 v[68:71], v[174:177], v[214:217], v[68:71]
	s_setprio 0
	s_barrier
; #define PG8_STAGE(bufoff, gbase, voff) do { _Pragma("unroll") for (int _i = 0; _i < 2; ++_i) \
;         __builtin_amdgcn_global_load_lds((const unsigned*)((const char*)(gbase) + (voff)[_i]), (PG8_LAS unsigned*)(lds + (bufoff) + ldsw + _i * 8192), 16, 0, 0); } while (0)
; #define PG8_LDA(dst, b, h) do { _Pragma("unroll") for (int m = 0; m < 4; ++m) _Pragma("unroll") for (int k = 0; k < 2; ++k) dst[m][k] = *(const PG8_LAS bf16x8*)(lds + PG8_SA(b, h) + aoff + m * 2048 + k * 1024); } while (0)
; #define PG8_LDB(dst, b, h) do { _Pragma("unroll") for (int n = 0; n < 2; ++n) _Pragma("unroll") for (int k = 0; k < 2; ++k) dst[n][k] = *(const PG8_LAS bf16x8*)(lds + PG8_SB(b, h) + boff + n * 2048 + k * 1024); } while (0)
; #define PG8_MMA(ai, bj, At, Bt) do { __builtin_amdgcn_s_setprio(1); _Pragma("unroll") for (int m = 0; m < 4; ++m) _Pragma("unroll") for (int n = 0; n < 2; ++n) _Pragma("unroll") for (int k = 0; k < 2; ++k) \
;         acc[ai][bj][m][n] = __builtin_amdgcn_mfma_f32_16x16x32_bf16(Bt[n][k], At[m][k], acc[ai][bj][m][n], 0, 0, 0); __builtin_amdgcn_s_setprio(0); } while (0)
; #define PG8_WAIT_V(n) asm volatile("s_waitcnt vmcnt(" #n ")" ::: "memory")
; #define PG8_WAIT_L(n) asm volatile("s_waitcnt lgkmcnt(" #n ")" ::: "memory")
; #define PG8_BAR __builtin_amdgcn_s_barrier()
; #define PG8_SCHED __builtin_amdgcn_sched_barrier(0)
; template <class Epi, class Sched, bool ALIGN_EPI = false, bool SP2 = false>
; __device__ __forceinline__ void gemm_phase(PG8_LAS unsigned char* lds, const Gemm g, const Sched& S, const Epi& E) {
;     ...
;             PG8_LDB(B0, 0, 0); PG8_LDB(B1, 0, 1); PG8_SCHED; PG8_LDA(At, 0, 0); PG8_STAGE(PG8_SA(1, 1), a1 + hstep, voffA);
;             PG8_WAIT_V(8); PG8_WAIT_L(0); PG8_BAR; PG8_MMA(0, 0, At, B0); PG8_MMA(0, 1, At, B1); PG8_BAR; PG8_SCHED;
;     ...
;             PG8_LDA(At, 1, 1); PG8_STAGE(PG8_SB(1, 0), b3, voffB); PG8_STAGE(PG8_SB(1, 1), b3 + hstep, voffB); PG8_STAGE(PG8_SA(1, 0), a3, voffA);
;             PG8_WAIT_V(8); PG8_WAIT_L(0); PG8_BAR; PG8_MMA(1, 0, At, B0); PG8_MMA(1, 1, At, B1); PG8_BAR; PG8_SCHED;
	s_add_i32 s40, s58, s43
	v_lshl_add_u64 v[144:145], v[144:145], 0, s[36:37]
	s_mov_b32 m0, s40
	ds_read_b128 v[178:181], v149 offset:49152
	ds_read_b128 v[182:185], v149 offset:50176
	ds_read_b128 v[186:189], v149 offset:51200
	ds_read_b128 v[190:193], v149 offset:52224
	ds_read_b128 v[202:205], v149 offset:53248
	ds_read_b128 v[206:209], v149 offset:54272
	ds_read_b128 v[210:213], v149 offset:55296
	ds_read_b128 v[214:217], v149 offset:56320
	global_load_lds_dwordx4 v[144:145], off
	s_add_i32 m0, s40, 0x2000
	s_add_u32 s22, s22, 0x40080
	v_lshl_add_u64 v[144:145], v[194:195], 0, s[36:37]
	s_addc_u32 s23, s23, 0
	s_add_i32 s40, s59, s43
	global_load_lds_dwordx4 v[144:145], off
	v_lshl_add_u64 v[144:145], s[22:23], 0, v[196:197]
	s_mov_b32 m0, s40
	s_nop 0
	global_load_lds_dwordx4 v[144:145], off
	v_lshl_add_u64 v[144:145], s[22:23], 0, v[32:33]
	s_add_i32 m0, s40, 0x2000
	s_nop 0
	global_load_lds_dwordx4 v[144:145], off
	v_lshl_add_u64 v[144:145], v[218:219], 0, s[36:37]
	s_mov_b32 m0, s49
	s_nop 0
	global_load_lds_dwordx4 v[144:145], off
	v_lshl_add_u64 v[144:145], v[220:221], 0, s[36:37]
	s_mov_b32 m0, s50
	s_nop 0
	global_load_lds_dwordx4 v[144:145], off
	s_waitcnt vmcnt(8)
	s_waitcnt lgkmcnt(0)
	v_mfma_f32_16x16x32_bf16 v[64:67], v[140:143], v[178:181], v[64:67]
	v_mfma_f32_16x16x32_bf16 v[60:63], v[154:157], v[178:181], v[60:63]
	v_mfma_f32_16x16x32_bf16 v[48:51], v[140:143], v[186:189], v[48:51]
	v_mfma_f32_16x16x32_bf16 v[44:47], v[154:157], v[186:189], v[44:47]
	s_barrier
	s_setprio 1
	v_mfma_f32_16x16x32_bf16 v[28:31], v[140:143], v[202:205], v[28:31]
	v_mfma_f32_16x16x32_bf16 v[24:27], v[154:157], v[202:205], v[24:27]
	v_mfma_f32_16x16x32_bf16 v[12:15], v[140:143], v[210:213], v[12:15]
	v_mfma_f32_16x16x32_bf16 v[8:11], v[154:157], v[210:213], v[8:11]
	v_mfma_f32_16x16x32_bf16 v[64:67], v[150:153], v[182:185], v[64:67]
	v_mfma_f32_16x16x32_bf16 v[60:63], v[158:161], v[182:185], v[60:63]
	v_mfma_f32_16x16x32_bf16 v[48:51], v[150:153], v[190:193], v[48:51]
	v_mfma_f32_16x16x32_bf16 v[44:47], v[158:161], v[190:193], v[44:47]
	v_mfma_f32_16x16x32_bf16 v[28:31], v[150:153], v[206:209], v[28:31]
	v_mfma_f32_16x16x32_bf16 v[24:27], v[158:161], v[206:209], v[24:27]
	v_mfma_f32_16x16x32_bf16 v[12:15], v[150:153], v[214:217], v[12:15]
	v_mfma_f32_16x16x32_bf16 v[8:11], v[158:161], v[214:217], v[8:11]
	s_setprio 0
	s_setprio 1
	v_mfma_f32_16x16x32_bf16 v[56:59], v[162:165], v[178:181], v[56:59]
	v_mfma_f32_16x16x32_bf16 v[52:55], v[170:173], v[178:181], v[52:55]
	v_mfma_f32_16x16x32_bf16 v[40:43], v[162:165], v[186:189], v[40:43]
	v_mfma_f32_16x16x32_bf16 v[36:39], v[170:173], v[186:189], v[36:39]
	v_mfma_f32_16x16x32_bf16 v[20:23], v[162:165], v[202:205], v[20:23]
	v_mfma_f32_16x16x32_bf16 v[16:19], v[170:173], v[202:205], v[16:19]
	v_mfma_f32_16x16x32_bf16 v[4:7], v[162:165], v[210:213], v[4:7]
	v_mfma_f32_16x16x32_bf16 v[0:3], v[170:173], v[210:213], v[0:3]
	v_mfma_f32_16x16x32_bf16 v[56:59], v[166:169], v[182:185], v[56:59]
	v_mfma_f32_16x16x32_bf16 v[52:55], v[174:177], v[182:185], v[52:55]
	v_mfma_f32_16x16x32_bf16 v[40:43], v[166:169], v[190:193], v[40:43]
	v_mfma_f32_16x16x32_bf16 v[36:39], v[174:177], v[190:193], v[36:39]
	v_mfma_f32_16x16x32_bf16 v[20:23], v[166:169], v[206:209], v[20:23]
	v_mfma_f32_16x16x32_bf16 v[16:19], v[174:177], v[206:209], v[16:19]
	v_mfma_f32_16x16x32_bf16 v[4:7], v[166:169], v[214:217], v[4:7]
	v_mfma_f32_16x16x32_bf16 v[0:3], v[174:177], v[214:217], v[0:3]
	s_setprio 0
	s_barrier
	s_add_i32 s57, s57, 2
	s_add_u32 s0, s0, 0x100
	s_addc_u32 s1, s1, 0
	s_add_u32 s55, s55, 0x100
	s_addc_u32 s56, s56, 0
	s_cmp_gt_u32 s57, 13
	s_cbranch_scc1 .Lkexit_sw
	s_cmp_eq_u32 s57, 12
	s_cbranch_scc0 .LBB0_623
	s_cmp_lg_u64 s[38:39], 0
	s_cbranch_scc1 .LBB0_623
.Ltail_sw:
	s_add_u32 s22, s0, 0xfffc0080
	s_addc_u32 s23, s1, -1
	s_add_i32 s58, 0, 0x10000
	s_cmp_eq_u32 s57, 12
	s_cselect_b32 s41, s17, s23
	s_cselect_b32 s40, s53, s22
	v_add_u32_e32 v144, s58, v147
	s_cselect_b32 s23, s15, s56
	s_cselect_b32 s22, s54, s55
	s_add_i32 s60, 0, 0x14000
	ds_read_b128 v[140:143], v144
	ds_read_b128 v[150:153], v144 offset:1024
	ds_read_b128 v[154:157], v144 offset:2048
	ds_read_b128 v[158:161], v144 offset:3072
	v_add_u32_e32 v144, s60, v147
	ds_read_b128 v[162:165], v144
	ds_read_b128 v[166:169], v144 offset:1024
	ds_read_b128 v[170:173], v144 offset:2048
	ds_read_b128 v[174:177], v144 offset:3072
	v_lshl_add_u64 v[144:145], s[0:1], 0, v[136:137]
	s_add_i32 m0, s44, 0xc000
	ds_read_b128 v[178:181], v149
	ds_read_b128 v[182:185], v149 offset:1024
	ds_read_b128 v[186:189], v149 offset:2048
	ds_read_b128 v[190:193], v149 offset:3072
	ds_read_b128 v[202:205], v149 offset:4096
	ds_read_b128 v[206:209], v149 offset:5120
	ds_read_b128 v[210:213], v149 offset:6144
	ds_read_b128 v[214:217], v149 offset:7168
	global_load_lds_dwordx4 v[144:145], off
	v_lshl_add_u64 v[144:145], s[0:1], 0, v[138:139]
	s_add_i32 m0, s44, 0xe000
	s_nop 0
	global_load_lds_dwordx4 v[144:145], off
	s_waitcnt vmcnt(8)
	s_waitcnt lgkmcnt(0)
	v_mfma_f32_16x16x32_bf16 v[128:131], v[140:143], v[178:181], v[128:131]
	v_mfma_f32_16x16x32_bf16 v[124:127], v[154:157], v[178:181], v[124:127]
	v_mfma_f32_16x16x32_bf16 v[112:115], v[140:143], v[186:189], v[112:115]
	v_mfma_f32_16x16x32_bf16 v[108:111], v[154:157], v[186:189], v[108:111]
	s_barrier
; #define PG8_STAGE(bufoff, gbase, voff) do { _Pragma("unroll") for (int _i = 0; _i < 2; ++_i) \
;         __builtin_amdgcn_global_load_lds((const unsigned*)((const char*)(gbase) + (voff)[_i]), (PG8_LAS unsigned*)(lds + (bufoff) + ldsw + _i * 8192), 16, 0, 0); } while (0)
; #define PG8_LDA(dst, b, h) do { _Pragma("unroll") for (int m = 0; m < 4; ++m) _Pragma("unroll") for (int k = 0; k < 2; ++k) dst[m][k] = *(const PG8_LAS bf16x8*)(lds + PG8_SA(b, h) + aoff + m * 2048 + k * 1024); } while (0)
; #define PG8_MMA(ai, bj, At, Bt) do { __builtin_amdgcn_s_setprio(1); _Pragma("unroll") for (int m = 0; m < 4; ++m) _Pragma("unroll") for (int n = 0; n < 2; ++n) _Pragma("unroll") for (int k = 0; k < 2; ++k) \
;         acc[ai][bj][m][n] = __builtin_amdgcn_mfma_f32_16x16x32_bf16(Bt[n][k], At[m][k], acc[ai][bj][m][n], 0, 0, 0); __builtin_amdgcn_s_setprio(0); } while (0)
; #define PG8_WAIT_V(n) asm volatile("s_waitcnt vmcnt(" #n ")" ::: "memory")
; #define PG8_WAIT_L(n) asm volatile("s_waitcnt lgkmcnt(" #n ")" ::: "memory")
; #define PG8_BAR __builtin_amdgcn_s_barrier()
; #define PG8_SCHED __builtin_amdgcn_sched_barrier(0)
; template <class Epi, class Sched, bool ALIGN_EPI = false, bool SP2 = false>
; __device__ __forceinline__ void gemm_phase(PG8_LAS unsigned char* lds, const Gemm g, const Sched& S, const Epi& E) {
;     ...
;             PG8_WAIT_V(8); PG8_WAIT_L(0); PG8_BAR; PG8_MMA(0, 0, At, B0); PG8_MMA(0, 1, At, B1); PG8_BAR; PG8_SCHED;
;             PG8_LDA(At, 0, 1); PG8_STAGE(PG8_SB(0, 0), b2, voffB); PG8_STAGE(PG8_SB(0, 1), b2 + hstep, voffB); PG8_STAGE(PG8_SA(0, 0), a2, voffA);
;             PG8_WAIT_V(8); PG8_WAIT_L(0); PG8_BAR; PG8_MMA(1, 0, At, B0); PG8_MMA(1, 1, At, B1); PG8_BAR; PG8_SCHED;
	s_setprio 1
	v_mfma_f32_16x16x32_bf16 v[96:99], v[140:143], v[202:205], v[96:99]
	v_mfma_f32_16x16x32_bf16 v[92:95], v[154:157], v[202:205], v[92:95]
	v_mfma_f32_16x16x32_bf16 v[80:83], v[140:143], v[210:213], v[80:83]
	v_mfma_f32_16x16x32_bf16 v[76:79], v[154:157], v[210:213], v[76:79]
	v_mfma_f32_16x16x32_bf16 v[128:131], v[150:153], v[182:185], v[128:131]
	v_mfma_f32_16x16x32_bf16 v[124:127], v[158:161], v[182:185], v[124:127]
	v_mfma_f32_16x16x32_bf16 v[112:115], v[150:153], v[190:193], v[112:115]
	v_mfma_f32_16x16x32_bf16 v[108:111], v[158:161], v[190:193], v[108:111]
	v_mfma_f32_16x16x32_bf16 v[96:99], v[150:153], v[206:209], v[96:99]
	v_mfma_f32_16x16x32_bf16 v[92:95], v[158:161], v[206:209], v[92:95]
	v_mfma_f32_16x16x32_bf16 v[80:83], v[150:153], v[214:217], v[80:83]
	v_mfma_f32_16x16x32_bf16 v[76:79], v[158:161], v[214:217], v[76:79]
	s_setprio 0
	s_setprio 1
	v_mfma_f32_16x16x32_bf16 v[120:123], v[162:165], v[178:181], v[120:123]
	v_mfma_f32_16x16x32_bf16 v[116:119], v[170:173], v[178:181], v[116:119]
	v_mfma_f32_16x16x32_bf16 v[104:107], v[162:165], v[186:189], v[104:107]
	v_mfma_f32_16x16x32_bf16 v[100:103], v[170:173], v[186:189], v[100:103]
	v_mfma_f32_16x16x32_bf16 v[88:91], v[162:165], v[202:205], v[88:91]
	v_mfma_f32_16x16x32_bf16 v[84:87], v[170:173], v[202:205], v[84:87]
	v_mfma_f32_16x16x32_bf16 v[72:75], v[162:165], v[210:213], v[72:75]
	v_mfma_f32_16x16x32_bf16 v[68:71], v[170:173], v[210:213], v[68:71]
	v_mfma_f32_16x16x32_bf16 v[120:123], v[166:169], v[182:185], v[120:123]
	v_mfma_f32_16x16x32_bf16 v[116:119], v[174:177], v[182:185], v[116:119]
	v_mfma_f32_16x16x32_bf16 v[104:107], v[166:169], v[190:193], v[104:107]
	v_mfma_f32_16x16x32_bf16 v[100:103], v[174:177], v[190:193], v[100:103]
	v_mfma_f32_16x16x32_bf16 v[88:91], v[166:169], v[206:209], v[88:91]
	v_mfma_f32_16x16x32_bf16 v[84:87], v[174:177], v[206:209], v[84:87]
	v_mfma_f32_16x16x32_bf16 v[72:75], v[166:169], v[214:217], v[72:75]
	v_mfma_f32_16x16x32_bf16 v[68:71], v[174:177], v[214:217], v[68:71]
	s_setprio 0
	s_barrier
	s_add_i32 s58, s58, s43
	v_lshl_add_u64 v[144:145], s[22:23], 0, v[196:197]
	s_mov_b32 m0, s58
	ds_read_b128 v[178:181], v149 offset:16384
	ds_read_b128 v[182:185], v149 offset:17408
	ds_read_b128 v[186:189], v149 offset:18432
	ds_read_b128 v[190:193], v149 offset:19456
	ds_read_b128 v[202:205], v149 offset:20480
	ds_read_b128 v[206:209], v149 offset:21504
	ds_read_b128 v[210:213], v149 offset:22528
	ds_read_b128 v[214:217], v149 offset:23552
	s_add_i32 m0, s58, 0x2000
	s_add_u32 s58, s22, 0x40000
	v_lshl_add_u64 v[194:195], s[22:23], 0, v[32:33]
	s_addc_u32 s59, s23, 0
	s_add_i32 s60, s60, s43
	v_lshl_add_u64 v[218:219], s[58:59], 0, v[196:197]
	s_mov_b32 m0, s60
	v_lshl_add_u64 v[220:221], s[40:41], 0, v[132:133]
	v_lshl_add_u64 v[218:219], s[58:59], 0, v[32:33]
	s_add_i32 m0, s60, 0x2000
	s_nop 0
	v_lshl_add_u64 v[218:219], s[40:41], 0, v[134:135]
	s_mov_b32 m0, s44
	s_nop 0
	s_mov_b32 m0, s45
	s_nop 0
	s_waitcnt vmcnt(2)
	s_waitcnt lgkmcnt(0)
	v_mfma_f32_16x16x32_bf16 v[64:67], v[140:143], v[178:181], v[64:67]
	v_mfma_f32_16x16x32_bf16 v[60:63], v[154:157], v[178:181], v[60:63]
	v_mfma_f32_16x16x32_bf16 v[48:51], v[140:143], v[186:189], v[48:51]
	v_mfma_f32_16x16x32_bf16 v[44:47], v[154:157], v[186:189], v[44:47]
	s_barrier
	s_setprio 1
	v_mfma_f32_16x16x32_bf16 v[28:31], v[140:143], v[202:205], v[28:31]
	v_mfma_f32_16x16x32_bf16 v[24:27], v[154:157], v[202:205], v[24:27]
	v_mfma_f32_16x16x32_bf16 v[12:15], v[140:143], v[210:213], v[12:15]
	v_mfma_f32_16x16x32_bf16 v[8:11], v[154:157], v[210:213], v[8:11]
	v_mfma_f32_16x16x32_bf16 v[64:67], v[150:153], v[182:185], v[64:67]
	v_mfma_f32_16x16x32_bf16 v[60:63], v[158:161], v[182:185], v[60:63]
	v_mfma_f32_16x16x32_bf16 v[48:51], v[150:153], v[190:193], v[48:51]
	v_mfma_f32_16x16x32_bf16 v[44:47], v[158:161], v[190:193], v[44:47]
	v_mfma_f32_16x16x32_bf16 v[28:31], v[150:153], v[206:209], v[28:31]
	v_mfma_f32_16x16x32_bf16 v[24:27], v[158:161], v[206:209], v[24:27]
	v_mfma_f32_16x16x32_bf16 v[12:15], v[150:153], v[214:217], v[12:15]
	v_mfma_f32_16x16x32_bf16 v[8:11], v[158:161], v[214:217], v[8:11]
	s_setprio 0
	s_setprio 1
	v_mfma_f32_16x16x32_bf16 v[56:59], v[162:165], v[178:181], v[56:59]
	v_mfma_f32_16x16x32_bf16 v[52:55], v[170:173], v[178:181], v[52:55]
	v_mfma_f32_16x16x32_bf16 v[40:43], v[162:165], v[186:189], v[40:43]
	v_mfma_f32_16x16x32_bf16 v[36:39], v[170:173], v[186:189], v[36:39]
	v_mfma_f32_16x16x32_bf16 v[20:23], v[162:165], v[202:205], v[20:23]
	v_mfma_f32_16x16x32_bf16 v[16:19], v[170:173], v[202:205], v[16:19]
	v_mfma_f32_16x16x32_bf16 v[4:7], v[162:165], v[210:213], v[4:7]
	v_mfma_f32_16x16x32_bf16 v[0:3], v[170:173], v[210:213], v[0:3]
	v_mfma_f32_16x16x32_bf16 v[56:59], v[166:169], v[182:185], v[56:59]
	v_mfma_f32_16x16x32_bf16 v[52:55], v[174:177], v[182:185], v[52:55]
	v_mfma_f32_16x16x32_bf16 v[40:43], v[166:169], v[190:193], v[40:43]
	v_mfma_f32_16x16x32_bf16 v[36:39], v[174:177], v[190:193], v[36:39]
	v_mfma_f32_16x16x32_bf16 v[20:23], v[166:169], v[206:209], v[20:23]
	v_mfma_f32_16x16x32_bf16 v[16:19], v[174:177], v[206:209], v[16:19]
	v_mfma_f32_16x16x32_bf16 v[4:7], v[166:169], v[214:217], v[4:7]
	v_mfma_f32_16x16x32_bf16 v[0:3], v[174:177], v[214:217], v[0:3]
	s_setprio 0
	s_barrier
; #define PG8_STAGE(bufoff, gbase, voff) do { _Pragma("unroll") for (int _i = 0; _i < 2; ++_i) \
;         __builtin_amdgcn_global_load_lds((const unsigned*)((const char*)(gbase) + (voff)[_i]), (PG8_LAS unsigned*)(lds + (bufoff) + ldsw + _i * 8192), 16, 0, 0); } while (0)
; #define PG8_LDA(dst, b, h) do { _Pragma("unroll") for (int m = 0; m < 4; ++m) _Pragma("unroll") for (int k = 0; k < 2; ++k) dst[m][k] = *(const PG8_LAS bf16x8*)(lds + PG8_SA(b, h) + aoff + m * 2048 + k * 1024); } while (0)
; #define PG8_LDB(dst, b, h) do { _Pragma("unroll") for (int n = 0; n < 2; ++n) _Pragma("unroll") for (int k = 0; k < 2; ++k) dst[n][k] = *(const PG8_LAS bf16x8*)(lds + PG8_SB(b, h) + boff + n * 2048 + k * 1024); } while (0)
; #define PG8_MMA(ai, bj, At, Bt) do { __builtin_amdgcn_s_setprio(1); _Pragma("unroll") for (int m = 0; m < 4; ++m) _Pragma("unroll") for (int n = 0; n < 2; ++n) _Pragma("unroll") for (int k = 0; k < 2; ++k) \
;         acc[ai][bj][m][n] = __builtin_amdgcn_mfma_f32_16x16x32_bf16(Bt[n][k], At[m][k], acc[ai][bj][m][n], 0, 0, 0); __builtin_amdgcn_s_setprio(0); } while (0)
; #define PG8_WAIT_V(n) asm volatile("s_waitcnt vmcnt(" #n ")" ::: "memory")
; #define PG8_WAIT_L(n) asm volatile("s_waitcnt lgkmcnt(" #n ")" ::: "memory")
; #define PG8_BAR __builtin_amdgcn_s_barrier()
; #define PG8_SCHED __builtin_amdgcn_sched_barrier(0)
; template <class Epi, class Sched, bool ALIGN_EPI = false, bool SP2 = false>
; __device__ __forceinline__ void gemm_phase(PG8_LAS unsigned char* lds, const Gemm g, const Sched& S, const Epi& E) {
;     ...
;             PG8_LDB(B0, 1, 0); PG8_LDB(B1, 1, 1); PG8_SCHED; PG8_LDA(At, 1, 0); PG8_STAGE(PG8_SA(0, 1), a2 + hstep, voffA);
;             PG8_WAIT_V(8); PG8_WAIT_L(0); PG8_BAR; PG8_MMA(0, 0, At, B0); PG8_MMA(0, 1, At, B1); PG8_BAR; PG8_SCHED;
;             PG8_LDA(At, 1, 1); PG8_STAGE(PG8_SB(1, 0), b3, voffB); PG8_STAGE(PG8_SB(1, 1), b3 + hstep, voffB); PG8_STAGE(PG8_SA(1, 0), a3, voffA);
;             PG8_WAIT_V(8); PG8_WAIT_L(0); PG8_BAR; PG8_MMA(1, 0, At, B0); PG8_MMA(1, 1, At, B1); PG8_BAR; PG8_SCHED;
	s_add_i32 s58, 0, 0x18000
	v_add_u32_e32 v146, s58, v147
	s_add_i32 s59, 0, 0x1c000
	ds_read_b128 v[140:143], v146
	ds_read_b128 v[150:153], v146 offset:1024
	ds_read_b128 v[154:157], v146 offset:2048
	ds_read_b128 v[158:161], v146 offset:3072
	v_add_u32_e32 v146, s59, v147
	ds_read_b128 v[162:165], v146
	ds_read_b128 v[166:169], v146 offset:1024
	ds_read_b128 v[170:173], v146 offset:2048
	ds_read_b128 v[174:177], v146 offset:3072
	s_add_u32 s40, s40, 0x40000
	s_addc_u32 s41, s41, 0
	s_mov_b32 m0, s46
	v_lshl_add_u64 v[222:223], s[40:41], 0, v[134:135]
	ds_read_b128 v[178:181], v149 offset:32768
	ds_read_b128 v[182:185], v149 offset:33792
	ds_read_b128 v[186:189], v149 offset:34816
	ds_read_b128 v[190:193], v149 offset:35840
	ds_read_b128 v[202:205], v149 offset:36864
	ds_read_b128 v[206:209], v149 offset:37888
	ds_read_b128 v[210:213], v149 offset:38912
	ds_read_b128 v[214:217], v149 offset:39936
	v_lshl_add_u64 v[222:223], s[40:41], 0, v[132:133]
	s_mov_b32 m0, s47
	s_nop 0
	s_waitcnt vmcnt(0)
	s_waitcnt lgkmcnt(0)
	v_mfma_f32_16x16x32_bf16 v[128:131], v[140:143], v[178:181], v[128:131]
	v_mfma_f32_16x16x32_bf16 v[124:127], v[154:157], v[178:181], v[124:127]
	v_mfma_f32_16x16x32_bf16 v[112:115], v[140:143], v[186:189], v[112:115]
	v_mfma_f32_16x16x32_bf16 v[108:111], v[154:157], v[186:189], v[108:111]
	s_barrier
	s_setprio 1
	v_mfma_f32_16x16x32_bf16 v[96:99], v[140:143], v[202:205], v[96:99]
	v_mfma_f32_16x16x32_bf16 v[92:95], v[154:157], v[202:205], v[92:95]
	v_mfma_f32_16x16x32_bf16 v[80:83], v[140:143], v[210:213], v[80:83]
	v_mfma_f32_16x16x32_bf16 v[76:79], v[154:157], v[210:213], v[76:79]
	v_mfma_f32_16x16x32_bf16 v[128:131], v[150:153], v[182:185], v[128:131]
	v_mfma_f32_16x16x32_bf16 v[124:127], v[158:161], v[182:185], v[124:127]
	v_mfma_f32_16x16x32_bf16 v[112:115], v[150:153], v[190:193], v[112:115]
	v_mfma_f32_16x16x32_bf16 v[108:111], v[158:161], v[190:193], v[108:111]
	v_mfma_f32_16x16x32_bf16 v[96:99], v[150:153], v[206:209], v[96:99]
	v_mfma_f32_16x16x32_bf16 v[92:95], v[158:161], v[206:209], v[92:95]
	v_mfma_f32_16x16x32_bf16 v[80:83], v[150:153], v[214:217], v[80:83]
	v_mfma_f32_16x16x32_bf16 v[76:79], v[158:161], v[214:217], v[76:79]
	s_setprio 0
	s_setprio 1
	v_mfma_f32_16x16x32_bf16 v[120:123], v[162:165], v[178:181], v[120:123]
	v_mfma_f32_16x16x32_bf16 v[116:119], v[170:173], v[178:181], v[116:119]
	v_mfma_f32_16x16x32_bf16 v[104:107], v[162:165], v[186:189], v[104:107]
	v_mfma_f32_16x16x32_bf16 v[100:103], v[170:173], v[186:189], v[100:103]
	v_mfma_f32_16x16x32_bf16 v[88:91], v[162:165], v[202:205], v[88:91]
	v_mfma_f32_16x16x32_bf16 v[84:87], v[170:173], v[202:205], v[84:87]
	v_mfma_f32_16x16x32_bf16 v[72:75], v[162:165], v[210:213], v[72:75]
	v_mfma_f32_16x16x32_bf16 v[68:71], v[170:173], v[210:213], v[68:71]
	v_mfma_f32_16x16x32_bf16 v[120:123], v[166:169], v[182:185], v[120:123]
	v_mfma_f32_16x16x32_bf16 v[116:119], v[174:177], v[182:185], v[116:119]
	v_mfma_f32_16x16x32_bf16 v[104:107], v[166:169], v[190:193], v[104:107]
	v_mfma_f32_16x16x32_bf16 v[100:103], v[174:177], v[190:193], v[100:103]
	v_mfma_f32_16x16x32_bf16 v[88:91], v[166:169], v[206:209], v[88:91]
	v_mfma_f32_16x16x32_bf16 v[84:87], v[174:177], v[206:209], v[84:87]
	v_mfma_f32_16x16x32_bf16 v[72:75], v[166:169], v[214:217], v[72:75]
	v_mfma_f32_16x16x32_bf16 v[68:71], v[174:177], v[214:217], v[68:71]
	s_setprio 0
	s_barrier
	s_add_i32 s40, s58, s43
	v_lshl_add_u64 v[144:145], v[144:145], 0, s[36:37]
	s_mov_b32 m0, s40
	ds_read_b128 v[178:181], v149 offset:49152
	ds_read_b128 v[182:185], v149 offset:50176
	ds_read_b128 v[186:189], v149 offset:51200
	ds_read_b128 v[190:193], v149 offset:52224
	ds_read_b128 v[202:205], v149 offset:53248
	ds_read_b128 v[206:209], v149 offset:54272
	ds_read_b128 v[210:213], v149 offset:55296
	ds_read_b128 v[214:217], v149 offset:56320
	s_add_i32 m0, s40, 0x2000
	s_add_u32 s22, s22, 0x40080
	v_lshl_add_u64 v[144:145], v[194:195], 0, s[36:37]
	s_addc_u32 s23, s23, 0
	s_add_i32 s40, s59, s43
	v_lshl_add_u64 v[144:145], s[22:23], 0, v[196:197]
	s_mov_b32 m0, s40
	s_nop 0
	v_lshl_add_u64 v[144:145], s[22:23], 0, v[32:33]
	s_add_i32 m0, s40, 0x2000
	s_nop 0
	v_lshl_add_u64 v[144:145], v[218:219], 0, s[36:37]
	s_mov_b32 m0, s49
	s_nop 0
	v_lshl_add_u64 v[144:145], v[220:221], 0, s[36:37]
	s_mov_b32 m0, s50
	s_nop 0
	s_waitcnt vmcnt(0)
	s_waitcnt lgkmcnt(0)
	v_mfma_f32_16x16x32_bf16 v[64:67], v[140:143], v[178:181], v[64:67]
	v_mfma_f32_16x16x32_bf16 v[60:63], v[154:157], v[178:181], v[60:63]
	v_mfma_f32_16x16x32_bf16 v[48:51], v[140:143], v[186:189], v[48:51]
	v_mfma_f32_16x16x32_bf16 v[44:47], v[154:157], v[186:189], v[44:47]
	s_barrier
	s_setprio 1
	v_mfma_f32_16x16x32_bf16 v[28:31], v[140:143], v[202:205], v[28:31]
	v_mfma_f32_16x16x32_bf16 v[24:27], v[154:157], v[202:205], v[24:27]
	v_mfma_f32_16x16x32_bf16 v[12:15], v[140:143], v[210:213], v[12:15]
	v_mfma_f32_16x16x32_bf16 v[8:11], v[154:157], v[210:213], v[8:11]
	v_mfma_f32_16x16x32_bf16 v[64:67], v[150:153], v[182:185], v[64:67]
	v_mfma_f32_16x16x32_bf16 v[60:63], v[158:161], v[182:185], v[60:63]
	v_mfma_f32_16x16x32_bf16 v[48:51], v[150:153], v[190:193], v[48:51]
	v_mfma_f32_16x16x32_bf16 v[44:47], v[158:161], v[190:193], v[44:47]
	v_mfma_f32_16x16x32_bf16 v[28:31], v[150:153], v[206:209], v[28:31]
	v_mfma_f32_16x16x32_bf16 v[24:27], v[158:161], v[206:209], v[24:27]
	v_mfma_f32_16x16x32_bf16 v[12:15], v[150:153], v[214:217], v[12:15]
	v_mfma_f32_16x16x32_bf16 v[8:11], v[158:161], v[214:217], v[8:11]
	s_setprio 0
	s_setprio 1
	v_mfma_f32_16x16x32_bf16 v[56:59], v[162:165], v[178:181], v[56:59]
	v_mfma_f32_16x16x32_bf16 v[52:55], v[170:173], v[178:181], v[52:55]
	v_mfma_f32_16x16x32_bf16 v[40:43], v[162:165], v[186:189], v[40:43]
	v_mfma_f32_16x16x32_bf16 v[36:39], v[170:173], v[186:189], v[36:39]
	v_mfma_f32_16x16x32_bf16 v[20:23], v[162:165], v[202:205], v[20:23]
	v_mfma_f32_16x16x32_bf16 v[16:19], v[170:173], v[202:205], v[16:19]
	v_mfma_f32_16x16x32_bf16 v[4:7], v[162:165], v[210:213], v[4:7]
	v_mfma_f32_16x16x32_bf16 v[0:3], v[170:173], v[210:213], v[0:3]
	v_mfma_f32_16x16x32_bf16 v[56:59], v[166:169], v[182:185], v[56:59]
	v_mfma_f32_16x16x32_bf16 v[52:55], v[174:177], v[182:185], v[52:55]
	v_mfma_f32_16x16x32_bf16 v[40:43], v[166:169], v[190:193], v[40:43]
	v_mfma_f32_16x16x32_bf16 v[36:39], v[174:177], v[190:193], v[36:39]
	v_mfma_f32_16x16x32_bf16 v[20:23], v[166:169], v[206:209], v[20:23]
	v_mfma_f32_16x16x32_bf16 v[16:19], v[174:177], v[206:209], v[16:19]
	v_mfma_f32_16x16x32_bf16 v[4:7], v[166:169], v[214:217], v[4:7]
	v_mfma_f32_16x16x32_bf16 v[0:3], v[174:177], v[214:217], v[0:3]
	s_setprio 0
	s_barrier
	s_add_i32 s57, s57, 2
	s_add_u32 s0, s0, 0x100
	s_addc_u32 s1, s1, 0
	s_add_u32 s55, s55, 0x100
	s_addc_u32 s56, s56, 0
